# v33 + GEMM K-loops: one static s_setprio 1 for waves 0-3 in front of each K-loop, dropped at loop exit
# speedup vs baseline: 1.0022x; 1.0004x over previous
; #define PG8_STAGE(bufoff, gbase, voff) do { _Pragma("unroll") for (int _i = 0; _i < 2; ++_i) \
;         __builtin_amdgcn_global_load_lds((const unsigned*)((const char*)(gbase) + (voff)[_i]), (PG8_LAS unsigned*)(lds + (bufoff) + ldsw + _i * 8192), 16, 0, 0); } while (0)
; #define PG8_LDA(dst, b, h) do { _Pragma("unroll") for (int m = 0; m < 4; ++m) _Pragma("unroll") for (int k = 0; k < 2; ++k) dst[m][k] = *(const PG8_LAS bf16x8*)(lds + PG8_SA(b, h) + aoff + m * 2048 + k * 1024); } while (0)
; #define PG8_LDB(dst, b, h) do { _Pragma("unroll") for (int n = 0; n < 2; ++n) _Pragma("unroll") for (int k = 0; k < 2; ++k) dst[n][k] = *(const PG8_LAS bf16x8*)(lds + PG8_SB(b, h) + boff + n * 2048 + k * 1024); } while (0)
; #define PG8_WAIT_V(n) asm volatile("s_waitcnt vmcnt(" #n ")" ::: "memory")
; #define PG8_WAIT_L(n) asm volatile("s_waitcnt lgkmcnt(" #n ")" ::: "memory")
; #define PG8_BAR __builtin_amdgcn_s_barrier()
; template <class Epi, class Sched, bool ALIGN_EPI = false, bool SP2 = false>
; __device__ __forceinline__ void gemm_phase(PG8_LAS unsigned char* lds, const Gemm g, const Sched& S, const Epi& E, int tid_in) {
;     ...
;         const char* nA = has_next ? (const char*)g.A + (size_t)nxt.pm * tstep : cA; const char* nB = has_next ? (const char*)g.Bt + (size_t)nxt.pn * tstep : cB;
;         for (int t = 0; t < nt; t += 2) {
;             if constexpr (Epi::MIDK) { if (t == Epi::MIDK_T) { if (wr == 0) PG8_BAR; E.mid(acc, cur, wr, wc, fr, fq); if (wr == 1) PG8_BAR; } }
;             const bool last = (t == nt - 2);
;             const char* a1 = cA + (size_t)(t + 1) * kstep;
;             const char* a2 = last ? nA : cA + (size_t)(t + 2) * kstep; const char* b2 = last ? nB : cB + (size_t)(t + 2) * kstep;
;             const char* a3 = a2 + kstep; const char* b3 = b2 + kstep;
;             if (last && has_next) S.a_ready(nxt);
;             if constexpr (SP2) {
;             PG8_LDB(B0, 0, 0); PG8_LDB(B1, 0, 1); PG8_SCHED; PG8_LDA(At, 0, 0); PG8_STAGE(PG8_SA(1, 1), a1 + hstep, voffA);
;             PG8_WAIT_V(8); PG8_WAIT_L(0); PG8_BAR; PG8_MMA(0, 0, At, B0); PG8_MMA(0, 1, At, B1); PG8_BAR; PG8_SCHED;
;             PG8_LDA(At, 0, 1); PG8_STAGE(PG8_SB(0, 0), b2, voffB); PG8_STAGE(PG8_SB(0, 1), b2 + hstep, voffB); PG8_STAGE(PG8_SA(0, 0), a2, voffA);
;             PG8_WAIT_V(8); PG8_WAIT_L(0); PG8_BAR; PG8_MMA(1, 0, At, B0); PG8_MMA(1, 1, At, B1); PG8_BAR; PG8_SCHED;
.LBB0_375:
	s_ashr_i32 s17, s16, 31
	s_lshl_b64 s[18:19], s[16:17], 19
	s_add_u32 s18, s0, s18
	s_addc_u32 s19, s1, s19
	s_and_b64 s[20:21], s[2:3], exec
	s_cselect_b32 s17, s19, s25
	s_cselect_b32 s52, s18, s24
	s_ashr_i32 s15, s14, 31
	s_lshl_b64 s[20:21], s[14:15], 19
	s_add_u32 s20, s30, s20
	s_addc_u32 s21, s31, s21
	s_and_b64 s[28:29], s[2:3], exec
	s_cselect_b32 s15, s21, s27
	s_cselect_b32 s53, s20, s26
	s_add_u32 s24, s24, 0x40080
	s_addc_u32 s25, s25, 0
	s_add_u32 s54, s26, 0x100
	s_addc_u32 s55, s27, 0
	s_mov_b32 s56, -2
	s_add_u32 s26, s24, 0xfffc0080
	s_addc_u32 s27, s25, -1
	s_cmp_eq_u32 s56, 12
	s_cselect_b32 s29, s17, s27
	s_cselect_b32 s28, s52, s26
	s_cselect_b32 s27, s15, s55
	s_cselect_b32 s26, s53, s54
	s_add_i32 m0, s23, 0xc000
	ds_read_b128 v[150:153], v147
	global_load_lds_dwordx4 v136, s[24:25]
	s_add_i32 m0, s23, 0xe000
	ds_read_b128 v[154:157], v147 offset:1024
	global_load_lds_dwordx4 v138, s[24:25]
	ds_read_b128 v[158:161], v147 offset:2048
	ds_read_b128 v[162:165], v147 offset:3072
	ds_read_b128 v[166:169], v148
	ds_read_b128 v[170:173], v148 offset:1024
	ds_read_b128 v[174:177], v148 offset:2048
	ds_read_b128 v[178:181], v148 offset:3072
	ds_read_b128 v[182:185], v149
	ds_read_b128 v[186:189], v149 offset:1024
	ds_read_b128 v[190:193], v149 offset:2048
	ds_read_b128 v[194:197], v149 offset:3072
	ds_read_b128 v[198:201], v149 offset:4096
	ds_read_b128 v[202:205], v149 offset:5120
	ds_read_b128 v[206:209], v149 offset:6144
	ds_read_b128 v[210:213], v149 offset:7168
	s_waitcnt vmcnt(8)
	s_waitcnt lgkmcnt(0)
	s_barrier
	v_mfma_f32_16x16x32_bf16 v[124:127], v[150:153], v[182:185], 0
	v_mfma_f32_16x16x32_bf16 v[120:123], v[158:161], v[182:185], 0
	v_mfma_f32_16x16x32_bf16 v[108:111], v[150:153], v[190:193], 0
	v_mfma_f32_16x16x32_bf16 v[104:107], v[158:161], v[190:193], 0
	v_mfma_f32_16x16x32_bf16 v[92:95], v[150:153], v[198:201], 0
	v_mfma_f32_16x16x32_bf16 v[88:91], v[158:161], v[198:201], 0
	v_mfma_f32_16x16x32_bf16 v[76:79], v[150:153], v[206:209], 0
	v_mfma_f32_16x16x32_bf16 v[72:75], v[158:161], v[206:209], 0
	v_mfma_f32_16x16x32_bf16 v[124:127], v[154:157], v[186:189], v[124:127]
	v_mfma_f32_16x16x32_bf16 v[120:123], v[162:165], v[186:189], v[120:123]
	v_mfma_f32_16x16x32_bf16 v[108:111], v[154:157], v[194:197], v[108:111]
	v_mfma_f32_16x16x32_bf16 v[104:107], v[162:165], v[194:197], v[104:107]
	v_mfma_f32_16x16x32_bf16 v[92:95], v[154:157], v[202:205], v[92:95]
	v_mfma_f32_16x16x32_bf16 v[88:91], v[162:165], v[202:205], v[88:91]
	v_mfma_f32_16x16x32_bf16 v[76:79], v[154:157], v[210:213], v[76:79]
	v_mfma_f32_16x16x32_bf16 v[72:75], v[162:165], v[210:213], v[72:75]
	v_mfma_f32_16x16x32_bf16 v[116:119], v[166:169], v[182:185], 0
	v_mfma_f32_16x16x32_bf16 v[112:115], v[174:177], v[182:185], 0
	v_mfma_f32_16x16x32_bf16 v[100:103], v[166:169], v[190:193], 0
	v_mfma_f32_16x16x32_bf16 v[96:99], v[174:177], v[190:193], 0
	v_mfma_f32_16x16x32_bf16 v[84:87], v[166:169], v[198:201], 0
	v_mfma_f32_16x16x32_bf16 v[80:83], v[174:177], v[198:201], 0
	v_mfma_f32_16x16x32_bf16 v[68:71], v[166:169], v[206:209], 0
	v_mfma_f32_16x16x32_bf16 v[64:67], v[174:177], v[206:209], 0
	v_mfma_f32_16x16x32_bf16 v[116:119], v[170:173], v[186:189], v[116:119]
	v_mfma_f32_16x16x32_bf16 v[112:115], v[178:181], v[186:189], v[112:115]
	v_mfma_f32_16x16x32_bf16 v[100:103], v[170:173], v[194:197], v[100:103]
	v_mfma_f32_16x16x32_bf16 v[96:99], v[178:181], v[194:197], v[96:99]
	v_mfma_f32_16x16x32_bf16 v[84:87], v[170:173], v[202:205], v[84:87]
	v_mfma_f32_16x16x32_bf16 v[80:83], v[178:181], v[202:205], v[80:83]
	v_mfma_f32_16x16x32_bf16 v[68:71], v[170:173], v[210:213], v[68:71]
	v_mfma_f32_16x16x32_bf16 v[64:67], v[178:181], v[210:213], v[64:67]
	s_barrier
	s_add_u32 s98, s26, s10
	s_addc_u32 s99, s27, s11
	s_add_u32 s100, s28, s10
	s_addc_u32 s101, s29, s11
	s_add_i32 s57, s48, s34
	s_mov_b32 m0, s57
	ds_read_b128 v[182:185], v149 offset:16384
	global_load_lds_dwordx4 v132, s[26:27]
	s_add_i32 m0, s57, 0x2000
	s_add_u32 s60, s26, 0x40000
	s_addc_u32 s61, s27, 0
	s_add_i32 s57, s49, s34
	global_load_lds_dwordx4 v128, s[26:27]
	s_mov_b32 m0, s57
	ds_read_b128 v[186:189], v149 offset:17408
	global_load_lds_dwordx4 v132, s[60:61]
	s_add_i32 m0, s57, 0x2000
	ds_read_b128 v[190:193], v149 offset:18432
	global_load_lds_dwordx4 v128, s[60:61]
	s_mov_b32 m0, s23
	ds_read_b128 v[194:197], v149 offset:19456
	global_load_lds_dwordx4 v134, s[28:29]
	s_mov_b32 m0, s37
	ds_read_b128 v[198:201], v149 offset:20480
	global_load_lds_dwordx4 v130, s[28:29]
	ds_read_b128 v[202:205], v149 offset:21504
	ds_read_b128 v[206:209], v149 offset:22528
	ds_read_b128 v[210:213], v149 offset:23552
	s_waitcnt vmcnt(8)
	s_waitcnt lgkmcnt(0)
	s_barrier
; #define PG8_STAGE(bufoff, gbase, voff) do { _Pragma("unroll") for (int _i = 0; _i < 2; ++_i) \
;         __builtin_amdgcn_global_load_lds((const unsigned*)((const char*)(gbase) + (voff)[_i]), (PG8_LAS unsigned*)(lds + (bufoff) + ldsw + _i * 8192), 16, 0, 0); } while (0)
; #define PG8_LDA(dst, b, h) do { _Pragma("unroll") for (int m = 0; m < 4; ++m) _Pragma("unroll") for (int k = 0; k < 2; ++k) dst[m][k] = *(const PG8_LAS bf16x8*)(lds + PG8_SA(b, h) + aoff + m * 2048 + k * 1024); } while (0)
; #define PG8_LDB(dst, b, h) do { _Pragma("unroll") for (int n = 0; n < 2; ++n) _Pragma("unroll") for (int k = 0; k < 2; ++k) dst[n][k] = *(const PG8_LAS bf16x8*)(lds + PG8_SB(b, h) + boff + n * 2048 + k * 1024); } while (0)
; #define PG8_MMA(ai, bj, At, Bt) do { __builtin_amdgcn_s_setprio(1); _Pragma("unroll") for (int m = 0; m < 4; ++m) _Pragma("unroll") for (int n = 0; n < 2; ++n) _Pragma("unroll") for (int k = 0; k < 2; ++k) \
;         acc[ai][bj][m][n] = __builtin_amdgcn_mfma_f32_16x16x32_bf16(Bt[n][k], At[m][k], acc[ai][bj][m][n], 0, 0, 0); __builtin_amdgcn_s_setprio(0); } while (0)
; #define PG8_WAIT_V(n) asm volatile("s_waitcnt vmcnt(" #n ")" ::: "memory")
; #define PG8_WAIT_L(n) asm volatile("s_waitcnt lgkmcnt(" #n ")" ::: "memory")
; #define PG8_BAR __builtin_amdgcn_s_barrier()
; #define PG8_SCHED __builtin_amdgcn_sched_barrier(0)
; template <class Epi, class Sched, bool ALIGN_EPI = false, bool SP2 = false>
; __device__ __forceinline__ void gemm_phase(PG8_LAS unsigned char* lds, const Gemm g, const Sched& S, const Epi& E, int tid_in) {
;     ...
;             PG8_WAIT_V(8); PG8_WAIT_L(0); PG8_BAR; PG8_MMA(1, 0, At, B0); PG8_MMA(1, 1, At, B1); PG8_BAR; PG8_SCHED;
;             PG8_LDB(B0, 1, 0); PG8_LDB(B1, 1, 1); PG8_SCHED; PG8_LDA(At, 1, 0); PG8_STAGE(PG8_SA(0, 1), a2 + hstep, voffA);
;             PG8_WAIT_V(8); PG8_WAIT_L(0); PG8_BAR; PG8_MMA(0, 0, At, B0); PG8_MMA(0, 1, At, B1); PG8_BAR; PG8_SCHED;
	v_mfma_f32_16x16x32_bf16 v[60:63], v[150:153], v[182:185], 0
	v_mfma_f32_16x16x32_bf16 v[56:59], v[158:161], v[182:185], 0
	v_mfma_f32_16x16x32_bf16 v[44:47], v[150:153], v[190:193], 0
	v_mfma_f32_16x16x32_bf16 v[40:43], v[158:161], v[190:193], 0
	v_mfma_f32_16x16x32_bf16 v[28:31], v[150:153], v[198:201], 0
	v_mfma_f32_16x16x32_bf16 v[24:27], v[158:161], v[198:201], 0
	v_mfma_f32_16x16x32_bf16 v[12:15], v[150:153], v[206:209], 0
	v_mfma_f32_16x16x32_bf16 v[8:11], v[158:161], v[206:209], 0
	v_mfma_f32_16x16x32_bf16 v[60:63], v[154:157], v[186:189], v[60:63]
	v_mfma_f32_16x16x32_bf16 v[56:59], v[162:165], v[186:189], v[56:59]
	v_mfma_f32_16x16x32_bf16 v[44:47], v[154:157], v[194:197], v[44:47]
	v_mfma_f32_16x16x32_bf16 v[40:43], v[162:165], v[194:197], v[40:43]
	v_mfma_f32_16x16x32_bf16 v[28:31], v[154:157], v[202:205], v[28:31]
	v_mfma_f32_16x16x32_bf16 v[24:27], v[162:165], v[202:205], v[24:27]
	v_mfma_f32_16x16x32_bf16 v[12:15], v[154:157], v[210:213], v[12:15]
	v_mfma_f32_16x16x32_bf16 v[8:11], v[162:165], v[210:213], v[8:11]
	v_mfma_f32_16x16x32_bf16 v[52:55], v[166:169], v[182:185], 0
	v_mfma_f32_16x16x32_bf16 v[48:51], v[174:177], v[182:185], 0
	v_mfma_f32_16x16x32_bf16 v[36:39], v[166:169], v[190:193], 0
	v_mfma_f32_16x16x32_bf16 v[32:35], v[174:177], v[190:193], 0
	v_mfma_f32_16x16x32_bf16 v[20:23], v[166:169], v[198:201], 0
	v_mfma_f32_16x16x32_bf16 v[16:19], v[174:177], v[198:201], 0
	v_mfma_f32_16x16x32_bf16 v[4:7], v[166:169], v[206:209], 0
	v_mfma_f32_16x16x32_bf16 v[0:3], v[174:177], v[206:209], 0
	v_mfma_f32_16x16x32_bf16 v[52:55], v[170:173], v[186:189], v[52:55]
	v_mfma_f32_16x16x32_bf16 v[48:51], v[178:181], v[186:189], v[48:51]
	v_mfma_f32_16x16x32_bf16 v[36:39], v[170:173], v[194:197], v[36:39]
	v_mfma_f32_16x16x32_bf16 v[32:35], v[178:181], v[194:197], v[32:35]
	v_mfma_f32_16x16x32_bf16 v[20:23], v[170:173], v[202:205], v[20:23]
	v_mfma_f32_16x16x32_bf16 v[16:19], v[178:181], v[202:205], v[16:19]
	v_mfma_f32_16x16x32_bf16 v[4:7], v[170:173], v[210:213], v[4:7]
	v_mfma_f32_16x16x32_bf16 v[0:3], v[178:181], v[210:213], v[0:3]
	s_barrier
	s_add_i32 s57, 0, 0x18000
	s_add_i32 s59, 0, 0x1c000
	s_add_u32 s28, s28, 0x40000
	s_addc_u32 s29, s29, 0
	s_mov_b32 m0, s38
	s_nop 0
	global_load_lds_dwordx4 v134, s[28:29]
	s_mov_b32 m0, s39
	s_nop 0
	global_load_lds_dwordx4 v130, s[28:29]
	v_add_u32_e32 v162, s57, v145
	v_add_u32_e32 v178, s59, v145
	ds_read_b128 v[150:153], v162
	ds_read_b128 v[154:157], v162 offset:1024
	ds_read_b128 v[158:161], v162 offset:2048
	ds_read_b128 v[162:165], v162 offset:3072
	ds_read_b128 v[166:169], v178
	ds_read_b128 v[170:173], v178 offset:1024
	ds_read_b128 v[174:177], v178 offset:2048
	ds_read_b128 v[178:181], v178 offset:3072
	ds_read_b128 v[182:185], v149 offset:32768
	ds_read_b128 v[186:189], v149 offset:33792
	ds_read_b128 v[190:193], v149 offset:34816
	ds_read_b128 v[194:197], v149 offset:35840
	ds_read_b128 v[198:201], v149 offset:36864
	ds_read_b128 v[202:205], v149 offset:37888
	ds_read_b128 v[206:209], v149 offset:38912
	ds_read_b128 v[210:213], v149 offset:39936
	s_waitcnt vmcnt(8)
	s_waitcnt lgkmcnt(0)
	s_barrier
	v_mfma_f32_16x16x32_bf16 v[124:127], v[150:153], v[182:185], v[124:127]
	v_mfma_f32_16x16x32_bf16 v[120:123], v[158:161], v[182:185], v[120:123]
	v_mfma_f32_16x16x32_bf16 v[108:111], v[150:153], v[190:193], v[108:111]
	v_mfma_f32_16x16x32_bf16 v[104:107], v[158:161], v[190:193], v[104:107]
	v_mfma_f32_16x16x32_bf16 v[92:95], v[150:153], v[198:201], v[92:95]
	v_mfma_f32_16x16x32_bf16 v[88:91], v[158:161], v[198:201], v[88:91]
	v_mfma_f32_16x16x32_bf16 v[76:79], v[150:153], v[206:209], v[76:79]
	v_mfma_f32_16x16x32_bf16 v[72:75], v[158:161], v[206:209], v[72:75]
	v_mfma_f32_16x16x32_bf16 v[124:127], v[154:157], v[186:189], v[124:127]
	v_mfma_f32_16x16x32_bf16 v[120:123], v[162:165], v[186:189], v[120:123]
	v_mfma_f32_16x16x32_bf16 v[108:111], v[154:157], v[194:197], v[108:111]
	v_mfma_f32_16x16x32_bf16 v[104:107], v[162:165], v[194:197], v[104:107]
	v_mfma_f32_16x16x32_bf16 v[92:95], v[154:157], v[202:205], v[92:95]
	v_mfma_f32_16x16x32_bf16 v[88:91], v[162:165], v[202:205], v[88:91]
	v_mfma_f32_16x16x32_bf16 v[76:79], v[154:157], v[210:213], v[76:79]
	v_mfma_f32_16x16x32_bf16 v[72:75], v[162:165], v[210:213], v[72:75]
	v_mfma_f32_16x16x32_bf16 v[116:119], v[166:169], v[182:185], v[116:119]
	v_mfma_f32_16x16x32_bf16 v[112:115], v[174:177], v[182:185], v[112:115]
	v_mfma_f32_16x16x32_bf16 v[100:103], v[166:169], v[190:193], v[100:103]
	v_mfma_f32_16x16x32_bf16 v[96:99], v[174:177], v[190:193], v[96:99]
	v_mfma_f32_16x16x32_bf16 v[84:87], v[166:169], v[198:201], v[84:87]
	v_mfma_f32_16x16x32_bf16 v[80:83], v[174:177], v[198:201], v[80:83]
	v_mfma_f32_16x16x32_bf16 v[68:71], v[166:169], v[206:209], v[68:71]
	v_mfma_f32_16x16x32_bf16 v[64:67], v[174:177], v[206:209], v[64:67]
	v_mfma_f32_16x16x32_bf16 v[116:119], v[170:173], v[186:189], v[116:119]
	v_mfma_f32_16x16x32_bf16 v[112:115], v[178:181], v[186:189], v[112:115]
	v_mfma_f32_16x16x32_bf16 v[100:103], v[170:173], v[194:197], v[100:103]
	v_mfma_f32_16x16x32_bf16 v[96:99], v[178:181], v[194:197], v[96:99]
	v_mfma_f32_16x16x32_bf16 v[84:87], v[170:173], v[202:205], v[84:87]
	v_mfma_f32_16x16x32_bf16 v[80:83], v[178:181], v[202:205], v[80:83]
	v_mfma_f32_16x16x32_bf16 v[68:71], v[170:173], v[210:213], v[68:71]
	v_mfma_f32_16x16x32_bf16 v[64:67], v[178:181], v[210:213], v[64:67]
	s_barrier
; #define PG8_STAGE(bufoff, gbase, voff) do { _Pragma("unroll") for (int _i = 0; _i < 2; ++_i) \
;         __builtin_amdgcn_global_load_lds((const unsigned*)((const char*)(gbase) + (voff)[_i]), (PG8_LAS unsigned*)(lds + (bufoff) + ldsw + _i * 8192), 16, 0, 0); } while (0)
; #define PG8_LDA(dst, b, h) do { _Pragma("unroll") for (int m = 0; m < 4; ++m) _Pragma("unroll") for (int k = 0; k < 2; ++k) dst[m][k] = *(const PG8_LAS bf16x8*)(lds + PG8_SA(b, h) + aoff + m * 2048 + k * 1024); } while (0)
; #define PG8_MMA(ai, bj, At, Bt) do { __builtin_amdgcn_s_setprio(1); _Pragma("unroll") for (int m = 0; m < 4; ++m) _Pragma("unroll") for (int n = 0; n < 2; ++n) _Pragma("unroll") for (int k = 0; k < 2; ++k) \
;         acc[ai][bj][m][n] = __builtin_amdgcn_mfma_f32_16x16x32_bf16(Bt[n][k], At[m][k], acc[ai][bj][m][n], 0, 0, 0); __builtin_amdgcn_s_setprio(0); } while (0)
; #define PG8_WAIT_V(n) asm volatile("s_waitcnt vmcnt(" #n ")" ::: "memory")
; #define PG8_WAIT_L(n) asm volatile("s_waitcnt lgkmcnt(" #n ")" ::: "memory")
; #define PG8_BAR __builtin_amdgcn_s_barrier()
; #define PG8_SCHED __builtin_amdgcn_sched_barrier(0)
; template <class Epi, class Sched, bool ALIGN_EPI = false, bool SP2 = false>
; __device__ __forceinline__ void gemm_phase(PG8_LAS unsigned char* lds, const Gemm g, const Sched& S, const Epi& E, int tid_in) {
;     ...
;             PG8_LDA(At, 1, 1); PG8_STAGE(PG8_SB(1, 0), b3, voffB); PG8_STAGE(PG8_SB(1, 1), b3 + hstep, voffB); PG8_STAGE(PG8_SA(1, 0), a3, voffA);
;             PG8_WAIT_V(8); PG8_WAIT_L(0); PG8_BAR; PG8_MMA(1, 0, At, B0); PG8_MMA(1, 1, At, B1); PG8_BAR; PG8_SCHED;
	s_add_i32 s28, s57, s34
	s_mov_b32 m0, s28
	ds_read_b128 v[182:185], v149 offset:49152
	global_load_lds_dwordx4 v132, s[98:99]
	s_add_i32 m0, s28, 0x2000
	s_add_u32 s26, s26, 0x40080
	s_addc_u32 s27, s27, 0
	s_add_i32 s28, s59, s34
	global_load_lds_dwordx4 v128, s[98:99]
	s_mov_b32 m0, s28
	ds_read_b128 v[186:189], v149 offset:50176
	global_load_lds_dwordx4 v132, s[26:27]
	s_add_i32 m0, s28, 0x2000
	ds_read_b128 v[190:193], v149 offset:51200
	global_load_lds_dwordx4 v128, s[26:27]
	s_mov_b32 m0, s44
	ds_read_b128 v[194:197], v149 offset:52224
	global_load_lds_dwordx4 v134, s[100:101]
	s_mov_b32 m0, s45
	ds_read_b128 v[198:201], v149 offset:53248
	global_load_lds_dwordx4 v130, s[100:101]
	ds_read_b128 v[202:205], v149 offset:54272
	ds_read_b128 v[206:209], v149 offset:55296
	ds_read_b128 v[210:213], v149 offset:56320
	s_waitcnt vmcnt(8)
	s_waitcnt lgkmcnt(0)
	s_barrier
	v_mfma_f32_16x16x32_bf16 v[60:63], v[150:153], v[182:185], v[60:63]
	v_mfma_f32_16x16x32_bf16 v[56:59], v[158:161], v[182:185], v[56:59]
	v_mfma_f32_16x16x32_bf16 v[44:47], v[150:153], v[190:193], v[44:47]
	v_mfma_f32_16x16x32_bf16 v[40:43], v[158:161], v[190:193], v[40:43]
	v_mfma_f32_16x16x32_bf16 v[28:31], v[150:153], v[198:201], v[28:31]
	v_mfma_f32_16x16x32_bf16 v[24:27], v[158:161], v[198:201], v[24:27]
	v_mfma_f32_16x16x32_bf16 v[12:15], v[150:153], v[206:209], v[12:15]
	v_mfma_f32_16x16x32_bf16 v[8:11], v[158:161], v[206:209], v[8:11]
	v_mfma_f32_16x16x32_bf16 v[60:63], v[154:157], v[186:189], v[60:63]
	v_mfma_f32_16x16x32_bf16 v[56:59], v[162:165], v[186:189], v[56:59]
	v_mfma_f32_16x16x32_bf16 v[44:47], v[154:157], v[194:197], v[44:47]
	v_mfma_f32_16x16x32_bf16 v[40:43], v[162:165], v[194:197], v[40:43]
	v_mfma_f32_16x16x32_bf16 v[28:31], v[154:157], v[202:205], v[28:31]
	v_mfma_f32_16x16x32_bf16 v[24:27], v[162:165], v[202:205], v[24:27]
	v_mfma_f32_16x16x32_bf16 v[12:15], v[154:157], v[210:213], v[12:15]
	v_mfma_f32_16x16x32_bf16 v[8:11], v[162:165], v[210:213], v[8:11]
	v_mfma_f32_16x16x32_bf16 v[52:55], v[166:169], v[182:185], v[52:55]
	v_mfma_f32_16x16x32_bf16 v[48:51], v[174:177], v[182:185], v[48:51]
	v_mfma_f32_16x16x32_bf16 v[36:39], v[166:169], v[190:193], v[36:39]
	v_mfma_f32_16x16x32_bf16 v[32:35], v[174:177], v[190:193], v[32:35]
	v_mfma_f32_16x16x32_bf16 v[20:23], v[166:169], v[198:201], v[20:23]
	v_mfma_f32_16x16x32_bf16 v[16:19], v[174:177], v[198:201], v[16:19]
	v_mfma_f32_16x16x32_bf16 v[4:7], v[166:169], v[206:209], v[4:7]
	v_mfma_f32_16x16x32_bf16 v[0:3], v[174:177], v[206:209], v[0:3]
	v_mfma_f32_16x16x32_bf16 v[52:55], v[170:173], v[186:189], v[52:55]
	v_mfma_f32_16x16x32_bf16 v[48:51], v[178:181], v[186:189], v[48:51]
	v_mfma_f32_16x16x32_bf16 v[36:39], v[170:173], v[194:197], v[36:39]
	v_mfma_f32_16x16x32_bf16 v[32:35], v[178:181], v[194:197], v[32:35]
	v_mfma_f32_16x16x32_bf16 v[20:23], v[170:173], v[202:205], v[20:23]
	v_mfma_f32_16x16x32_bf16 v[16:19], v[178:181], v[202:205], v[16:19]
	v_mfma_f32_16x16x32_bf16 v[4:7], v[170:173], v[210:213], v[4:7]
	v_mfma_f32_16x16x32_bf16 v[0:3], v[178:181], v[210:213], v[0:3]
	s_barrier
	s_add_i32 s56, s56, 2
	s_add_u32 s24, s24, 0x100
	s_addc_u32 s25, s25, 0
	s_add_u32 s54, s54, 0x100
	s_addc_u32 s55, s55, 0
	v_readlane_b32 s98, v248, 0
	s_nop 3
	s_cmp_ge_u32 s98, 0x100
	s_cbranch_scc1 .Lgprio_skip_0
	s_setprio 1

; #define PG8_STAGE(bufoff, gbase, voff) do { _Pragma("unroll") for (int _i = 0; _i < 2; ++_i) \
;         __builtin_amdgcn_global_load_lds((const unsigned*)((const char*)(gbase) + (voff)[_i]), (PG8_LAS unsigned*)(lds + (bufoff) + ldsw + _i * 8192), 16, 0, 0); } while (0)
; #define PG8_LDA(dst, b, h) do { _Pragma("unroll") for (int m = 0; m < 4; ++m) _Pragma("unroll") for (int k = 0; k < 2; ++k) dst[m][k] = *(const PG8_LAS bf16x8*)(lds + PG8_SA(b, h) + aoff + m * 2048 + k * 1024); } while (0)
; #define PG8_LDB(dst, b, h) do { _Pragma("unroll") for (int n = 0; n < 2; ++n) _Pragma("unroll") for (int k = 0; k < 2; ++k) dst[n][k] = *(const PG8_LAS bf16x8*)(lds + PG8_SB(b, h) + boff + n * 2048 + k * 1024); } while (0)
; #define PG8_MMA(ai, bj, At, Bt) do { __builtin_amdgcn_s_setprio(1); _Pragma("unroll") for (int m = 0; m < 4; ++m) _Pragma("unroll") for (int n = 0; n < 2; ++n) _Pragma("unroll") for (int k = 0; k < 2; ++k) \
;         acc[ai][bj][m][n] = __builtin_amdgcn_mfma_f32_16x16x32_bf16(Bt[n][k], At[m][k], acc[ai][bj][m][n], 0, 0, 0); __builtin_amdgcn_s_setprio(0); } while (0)
; #define PG8_WAIT_V(n) asm volatile("s_waitcnt vmcnt(" #n ")" ::: "memory")
; #define PG8_WAIT_L(n) asm volatile("s_waitcnt lgkmcnt(" #n ")" ::: "memory")
; template <class Epi, class Sched, bool ALIGN_EPI = false, bool SP2 = false>
; __device__ __forceinline__ void gemm_phase(PG8_LAS unsigned char* lds, const Gemm g, const Sched& S, const Epi& E, int tid_in) {
;     ...
;             const bool last = (t == nt - 2);
;             const char* a1 = cA + (size_t)(t + 1) * kstep;
;             const char* a2 = last ? nA : cA + (size_t)(t + 2) * kstep; const char* b2 = last ? nB : cB + (size_t)(t + 2) * kstep;
;             const char* a3 = a2 + kstep; const char* b3 = b2 + kstep;
;             if (last && has_next) S.a_ready(nxt);
;             if constexpr (SP2) {
;             PG8_LDB(B0, 0, 0); PG8_LDB(B1, 0, 1); PG8_SCHED; PG8_LDA(At, 0, 0); PG8_STAGE(PG8_SA(1, 1), a1 + hstep, voffA);
;             PG8_WAIT_V(8); PG8_WAIT_L(0); PG8_BAR; PG8_MMA(0, 0, At, B0); PG8_MMA(0, 1, At, B1); PG8_BAR; PG8_SCHED;
;             PG8_LDA(At, 0, 1); PG8_STAGE(PG8_SB(0, 0), b2, voffB); PG8_STAGE(PG8_SB(0, 1), b2 + hstep, voffB); PG8_STAGE(PG8_SA(0, 0), a2, voffA);
;             PG8_WAIT_V(8); PG8_WAIT_L(0); PG8_BAR; PG8_MMA(1, 0, At, B0); PG8_MMA(1, 1, At, B1); PG8_BAR; PG8_SCHED;
.LBB0_460:
	s_add_u32 s12, s50, 0x100
	s_addc_u32 s75, s51, 0
	s_mov_b32 s76, -2
	s_waitcnt lgkmcnt(0)
	s_add_u32 s6, s48, 0x100
	s_addc_u32 s7, s49, 0
	s_cmp_eq_u32 s76, 40
	s_cselect_b32 s53, s45, s7
	s_cselect_b32 s52, s44, s6
	s_cselect_b32 s51, s47, s75
	s_cselect_b32 s50, s46, s12
	s_add_i32 m0, s60, 0xc000
	ds_read_b128 v[128:131], v236
	global_load_lds_dwordx4 v200, s[48:49]
	s_add_i32 m0, s60, 0xe000
	ds_read_b128 v[132:135], v236 offset:1024
	global_load_lds_dwordx4 v202, s[48:49]
	ds_read_b128 v[136:139], v236 offset:2048
	ds_read_b128 v[140:143], v236 offset:3072
	ds_read_b128 v[144:147], v237
	ds_read_b128 v[148:151], v237 offset:1024
	ds_read_b128 v[152:155], v237 offset:2048
	ds_read_b128 v[156:159], v237 offset:3072
	ds_read_b128 v[160:163], v238
	ds_read_b128 v[164:167], v238 offset:1024
	ds_read_b128 v[168:171], v238 offset:2048
	ds_read_b128 v[172:175], v238 offset:3072
	ds_read_b128 v[176:179], v238 offset:4096
	ds_read_b128 v[180:183], v238 offset:5120
	ds_read_b128 v[184:187], v238 offset:6144
	ds_read_b128 v[188:191], v238 offset:7168
	s_waitcnt vmcnt(8)
	s_waitcnt lgkmcnt(0)
	s_barrier
	v_mfma_f32_16x16x32_bf16 v[124:127], v[128:131], v[160:163], 0
	v_mfma_f32_16x16x32_bf16 v[120:123], v[136:139], v[160:163], 0
	v_mfma_f32_16x16x32_bf16 v[108:111], v[128:131], v[168:171], 0
	v_mfma_f32_16x16x32_bf16 v[104:107], v[136:139], v[168:171], 0
	v_mfma_f32_16x16x32_bf16 v[92:95], v[128:131], v[176:179], 0
	v_mfma_f32_16x16x32_bf16 v[88:91], v[136:139], v[176:179], 0
	v_mfma_f32_16x16x32_bf16 v[76:79], v[128:131], v[184:187], 0
	v_mfma_f32_16x16x32_bf16 v[72:75], v[136:139], v[184:187], 0
	v_mfma_f32_16x16x32_bf16 v[124:127], v[132:135], v[164:167], v[124:127]
	v_mfma_f32_16x16x32_bf16 v[120:123], v[140:143], v[164:167], v[120:123]
	v_mfma_f32_16x16x32_bf16 v[108:111], v[132:135], v[172:175], v[108:111]
	v_mfma_f32_16x16x32_bf16 v[104:107], v[140:143], v[172:175], v[104:107]
	v_mfma_f32_16x16x32_bf16 v[92:95], v[132:135], v[180:183], v[92:95]
	v_mfma_f32_16x16x32_bf16 v[88:91], v[140:143], v[180:183], v[88:91]
	v_mfma_f32_16x16x32_bf16 v[76:79], v[132:135], v[188:191], v[76:79]
	v_mfma_f32_16x16x32_bf16 v[72:75], v[140:143], v[188:191], v[72:75]
	v_mfma_f32_16x16x32_bf16 v[116:119], v[144:147], v[160:163], 0
	v_mfma_f32_16x16x32_bf16 v[112:115], v[152:155], v[160:163], 0
	v_mfma_f32_16x16x32_bf16 v[100:103], v[144:147], v[168:171], 0
	v_mfma_f32_16x16x32_bf16 v[96:99], v[152:155], v[168:171], 0
	v_mfma_f32_16x16x32_bf16 v[84:87], v[144:147], v[176:179], 0
	v_mfma_f32_16x16x32_bf16 v[80:83], v[152:155], v[176:179], 0
	v_mfma_f32_16x16x32_bf16 v[68:71], v[144:147], v[184:187], 0
	v_mfma_f32_16x16x32_bf16 v[64:67], v[152:155], v[184:187], 0
	v_mfma_f32_16x16x32_bf16 v[116:119], v[148:151], v[164:167], v[116:119]
	v_mfma_f32_16x16x32_bf16 v[112:115], v[156:159], v[164:167], v[112:115]
	v_mfma_f32_16x16x32_bf16 v[100:103], v[148:151], v[172:175], v[100:103]
	v_mfma_f32_16x16x32_bf16 v[96:99], v[156:159], v[172:175], v[96:99]
	v_mfma_f32_16x16x32_bf16 v[84:87], v[148:151], v[180:183], v[84:87]
	v_mfma_f32_16x16x32_bf16 v[80:83], v[156:159], v[180:183], v[80:83]
	v_mfma_f32_16x16x32_bf16 v[68:71], v[148:151], v[188:191], v[68:71]
	v_mfma_f32_16x16x32_bf16 v[64:67], v[156:159], v[188:191], v[64:67]
	s_barrier
	s_add_u32 s98, s50, s22
	s_addc_u32 s99, s51, s23
	s_add_u32 s100, s52, s22
	s_addc_u32 s101, s53, s23
	s_add_i32 s48, s70, s59
	s_mov_b32 m0, s48
	ds_read_b128 v[160:163], v238 offset:16384
	global_load_lds_dwordx4 v194, s[50:51]
	s_add_i32 m0, s48, 0x2000
	s_add_u32 s48, s50, 0xb0000
	s_addc_u32 s49, s51, 0
	s_add_i32 s77, s71, s59
	global_load_lds_dwordx4 v198, s[50:51]
	s_mov_b32 m0, s77
	ds_read_b128 v[164:167], v238 offset:17408
	global_load_lds_dwordx4 v194, s[48:49]
	s_add_i32 m0, s77, 0x2000
	ds_read_b128 v[168:171], v238 offset:18432
	global_load_lds_dwordx4 v198, s[48:49]
	s_mov_b32 m0, s60
	ds_read_b128 v[172:175], v238 offset:19456
	global_load_lds_dwordx4 v192, s[52:53]
	s_mov_b32 m0, s61
	ds_read_b128 v[176:179], v238 offset:20480
	global_load_lds_dwordx4 v196, s[52:53]
	ds_read_b128 v[180:183], v238 offset:21504
	ds_read_b128 v[184:187], v238 offset:22528
	ds_read_b128 v[188:191], v238 offset:23552
	s_waitcnt vmcnt(8)
	s_waitcnt lgkmcnt(0)
	s_barrier
	v_mfma_f32_16x16x32_bf16 v[60:63], v[128:131], v[160:163], 0
	v_mfma_f32_16x16x32_bf16 v[56:59], v[136:139], v[160:163], 0
	v_mfma_f32_16x16x32_bf16 v[44:47], v[128:131], v[168:171], 0
	v_mfma_f32_16x16x32_bf16 v[40:43], v[136:139], v[168:171], 0
	v_mfma_f32_16x16x32_bf16 v[28:31], v[128:131], v[176:179], 0
	v_mfma_f32_16x16x32_bf16 v[24:27], v[136:139], v[176:179], 0
	v_mfma_f32_16x16x32_bf16 v[12:15], v[128:131], v[184:187], 0
	v_mfma_f32_16x16x32_bf16 v[8:11], v[136:139], v[184:187], 0
	v_mfma_f32_16x16x32_bf16 v[60:63], v[132:135], v[164:167], v[60:63]
	v_mfma_f32_16x16x32_bf16 v[56:59], v[140:143], v[164:167], v[56:59]
	v_mfma_f32_16x16x32_bf16 v[44:47], v[132:135], v[172:175], v[44:47]
	v_mfma_f32_16x16x32_bf16 v[40:43], v[140:143], v[172:175], v[40:43]
	v_mfma_f32_16x16x32_bf16 v[28:31], v[132:135], v[180:183], v[28:31]
	v_mfma_f32_16x16x32_bf16 v[24:27], v[140:143], v[180:183], v[24:27]
	v_mfma_f32_16x16x32_bf16 v[12:15], v[132:135], v[188:191], v[12:15]
	v_mfma_f32_16x16x32_bf16 v[8:11], v[140:143], v[188:191], v[8:11]
	v_mfma_f32_16x16x32_bf16 v[52:55], v[144:147], v[160:163], 0
	v_mfma_f32_16x16x32_bf16 v[48:51], v[152:155], v[160:163], 0
	v_mfma_f32_16x16x32_bf16 v[36:39], v[144:147], v[168:171], 0
	v_mfma_f32_16x16x32_bf16 v[32:35], v[152:155], v[168:171], 0
	v_mfma_f32_16x16x32_bf16 v[20:23], v[144:147], v[176:179], 0
	v_mfma_f32_16x16x32_bf16 v[16:19], v[152:155], v[176:179], 0
	v_mfma_f32_16x16x32_bf16 v[4:7], v[144:147], v[184:187], 0
	v_mfma_f32_16x16x32_bf16 v[0:3], v[152:155], v[184:187], 0
	v_mfma_f32_16x16x32_bf16 v[52:55], v[148:151], v[164:167], v[52:55]
	v_mfma_f32_16x16x32_bf16 v[48:51], v[156:159], v[164:167], v[48:51]
	v_mfma_f32_16x16x32_bf16 v[36:39], v[148:151], v[172:175], v[36:39]
	v_mfma_f32_16x16x32_bf16 v[32:35], v[156:159], v[172:175], v[32:35]
	v_mfma_f32_16x16x32_bf16 v[20:23], v[148:151], v[180:183], v[20:23]
	v_mfma_f32_16x16x32_bf16 v[16:19], v[156:159], v[180:183], v[16:19]
	v_mfma_f32_16x16x32_bf16 v[4:7], v[148:151], v[188:191], v[4:7]
	v_mfma_f32_16x16x32_bf16 v[0:3], v[156:159], v[188:191], v[0:3]
	s_barrier
; #define PG8_STAGE(bufoff, gbase, voff) do { _Pragma("unroll") for (int _i = 0; _i < 2; ++_i) \
;         __builtin_amdgcn_global_load_lds((const unsigned*)((const char*)(gbase) + (voff)[_i]), (PG8_LAS unsigned*)(lds + (bufoff) + ldsw + _i * 8192), 16, 0, 0); } while (0)
; #define PG8_LDA(dst, b, h) do { _Pragma("unroll") for (int m = 0; m < 4; ++m) _Pragma("unroll") for (int k = 0; k < 2; ++k) dst[m][k] = *(const PG8_LAS bf16x8*)(lds + PG8_SA(b, h) + aoff + m * 2048 + k * 1024); } while (0)
; #define PG8_LDB(dst, b, h) do { _Pragma("unroll") for (int n = 0; n < 2; ++n) _Pragma("unroll") for (int k = 0; k < 2; ++k) dst[n][k] = *(const PG8_LAS bf16x8*)(lds + PG8_SB(b, h) + boff + n * 2048 + k * 1024); } while (0)
; #define PG8_MMA(ai, bj, At, Bt) do { __builtin_amdgcn_s_setprio(1); _Pragma("unroll") for (int m = 0; m < 4; ++m) _Pragma("unroll") for (int n = 0; n < 2; ++n) _Pragma("unroll") for (int k = 0; k < 2; ++k) \
;         acc[ai][bj][m][n] = __builtin_amdgcn_mfma_f32_16x16x32_bf16(Bt[n][k], At[m][k], acc[ai][bj][m][n], 0, 0, 0); __builtin_amdgcn_s_setprio(0); } while (0)
; #define PG8_WAIT_V(n) asm volatile("s_waitcnt vmcnt(" #n ")" ::: "memory")
; #define PG8_WAIT_L(n) asm volatile("s_waitcnt lgkmcnt(" #n ")" ::: "memory")
; #define PG8_BAR __builtin_amdgcn_s_barrier()
; #define PG8_SCHED __builtin_amdgcn_sched_barrier(0)
; template <class Epi, class Sched, bool ALIGN_EPI = false, bool SP2 = false>
; __device__ __forceinline__ void gemm_phase(PG8_LAS unsigned char* lds, const Gemm g, const Sched& S, const Epi& E, int tid_in) {
;     ...
;             PG8_LDB(B0, 1, 0); PG8_LDB(B1, 1, 1); PG8_SCHED; PG8_LDA(At, 1, 0); PG8_STAGE(PG8_SA(0, 1), a2 + hstep, voffA);
;             PG8_WAIT_V(8); PG8_WAIT_L(0); PG8_BAR; PG8_MMA(0, 0, At, B0); PG8_MMA(0, 1, At, B1); PG8_BAR; PG8_SCHED;
;             PG8_LDA(At, 1, 1); PG8_STAGE(PG8_SB(1, 0), b3, voffB); PG8_STAGE(PG8_SB(1, 1), b3 + hstep, voffB); PG8_STAGE(PG8_SA(1, 0), a3, voffA);
;             PG8_WAIT_V(8); PG8_WAIT_L(0); PG8_BAR; PG8_MMA(1, 0, At, B0); PG8_MMA(1, 1, At, B1); PG8_BAR; PG8_SCHED;
	s_add_i32 s77, 0, 0x18000
	s_add_i32 s78, 0, 0x1c000
	s_add_u32 s48, s52, 0xb0000
	s_addc_u32 s49, s53, 0
	s_mov_b32 m0, s62
	s_nop 0
	global_load_lds_dwordx4 v192, s[48:49]
	s_mov_b32 m0, s63
	s_nop 0
	global_load_lds_dwordx4 v196, s[48:49]
	v_add_u32_e32 v140, s77, v232
	v_add_u32_e32 v156, s78, v232
	ds_read_b128 v[128:131], v140
	ds_read_b128 v[132:135], v140 offset:1024
	ds_read_b128 v[136:139], v140 offset:2048
	ds_read_b128 v[140:143], v140 offset:3072
	ds_read_b128 v[144:147], v156
	ds_read_b128 v[148:151], v156 offset:1024
	ds_read_b128 v[152:155], v156 offset:2048
	ds_read_b128 v[156:159], v156 offset:3072
	ds_read_b128 v[160:163], v238 offset:32768
	ds_read_b128 v[164:167], v238 offset:33792
	ds_read_b128 v[168:171], v238 offset:34816
	ds_read_b128 v[172:175], v238 offset:35840
	ds_read_b128 v[176:179], v238 offset:36864
	ds_read_b128 v[180:183], v238 offset:37888
	ds_read_b128 v[184:187], v238 offset:38912
	ds_read_b128 v[188:191], v238 offset:39936
	s_waitcnt vmcnt(8)
	s_waitcnt lgkmcnt(0)
	s_barrier
	v_mfma_f32_16x16x32_bf16 v[124:127], v[128:131], v[160:163], v[124:127]
	v_mfma_f32_16x16x32_bf16 v[120:123], v[136:139], v[160:163], v[120:123]
	v_mfma_f32_16x16x32_bf16 v[108:111], v[128:131], v[168:171], v[108:111]
	v_mfma_f32_16x16x32_bf16 v[104:107], v[136:139], v[168:171], v[104:107]
	v_mfma_f32_16x16x32_bf16 v[92:95], v[128:131], v[176:179], v[92:95]
	v_mfma_f32_16x16x32_bf16 v[88:91], v[136:139], v[176:179], v[88:91]
	v_mfma_f32_16x16x32_bf16 v[76:79], v[128:131], v[184:187], v[76:79]
	v_mfma_f32_16x16x32_bf16 v[72:75], v[136:139], v[184:187], v[72:75]
	v_mfma_f32_16x16x32_bf16 v[124:127], v[132:135], v[164:167], v[124:127]
	v_mfma_f32_16x16x32_bf16 v[120:123], v[140:143], v[164:167], v[120:123]
	v_mfma_f32_16x16x32_bf16 v[108:111], v[132:135], v[172:175], v[108:111]
	v_mfma_f32_16x16x32_bf16 v[104:107], v[140:143], v[172:175], v[104:107]
	v_mfma_f32_16x16x32_bf16 v[92:95], v[132:135], v[180:183], v[92:95]
	v_mfma_f32_16x16x32_bf16 v[88:91], v[140:143], v[180:183], v[88:91]
	v_mfma_f32_16x16x32_bf16 v[76:79], v[132:135], v[188:191], v[76:79]
	v_mfma_f32_16x16x32_bf16 v[72:75], v[140:143], v[188:191], v[72:75]
	v_mfma_f32_16x16x32_bf16 v[116:119], v[144:147], v[160:163], v[116:119]
	v_mfma_f32_16x16x32_bf16 v[112:115], v[152:155], v[160:163], v[112:115]
	v_mfma_f32_16x16x32_bf16 v[100:103], v[144:147], v[168:171], v[100:103]
	v_mfma_f32_16x16x32_bf16 v[96:99], v[152:155], v[168:171], v[96:99]
	v_mfma_f32_16x16x32_bf16 v[84:87], v[144:147], v[176:179], v[84:87]
	v_mfma_f32_16x16x32_bf16 v[80:83], v[152:155], v[176:179], v[80:83]
	v_mfma_f32_16x16x32_bf16 v[68:71], v[144:147], v[184:187], v[68:71]
	v_mfma_f32_16x16x32_bf16 v[64:67], v[152:155], v[184:187], v[64:67]
	v_mfma_f32_16x16x32_bf16 v[116:119], v[148:151], v[164:167], v[116:119]
	v_mfma_f32_16x16x32_bf16 v[112:115], v[156:159], v[164:167], v[112:115]
	v_mfma_f32_16x16x32_bf16 v[100:103], v[148:151], v[172:175], v[100:103]
	v_mfma_f32_16x16x32_bf16 v[96:99], v[156:159], v[172:175], v[96:99]
	v_mfma_f32_16x16x32_bf16 v[84:87], v[148:151], v[180:183], v[84:87]
	v_mfma_f32_16x16x32_bf16 v[80:83], v[156:159], v[180:183], v[80:83]
	v_mfma_f32_16x16x32_bf16 v[68:71], v[148:151], v[188:191], v[68:71]
	v_mfma_f32_16x16x32_bf16 v[64:67], v[156:159], v[188:191], v[64:67]
	s_barrier
	s_add_i32 s48, s77, s59
	s_mov_b32 m0, s48
	ds_read_b128 v[160:163], v238 offset:49152
	global_load_lds_dwordx4 v194, s[98:99]
	s_add_i32 m0, s48, 0x2000
	s_add_u32 s48, s50, 0xb0080
	s_addc_u32 s49, s51, 0
	s_add_i32 s50, s78, s59
	global_load_lds_dwordx4 v198, s[98:99]
	s_mov_b32 m0, s50
	ds_read_b128 v[164:167], v238 offset:50176
	global_load_lds_dwordx4 v194, s[48:49]
	s_add_i32 m0, s50, 0x2000
	ds_read_b128 v[168:171], v238 offset:51200
	global_load_lds_dwordx4 v198, s[48:49]
	s_mov_b32 m0, s65
	ds_read_b128 v[172:175], v238 offset:52224
	global_load_lds_dwordx4 v192, s[100:101]
	s_mov_b32 m0, s67
	ds_read_b128 v[176:179], v238 offset:53248
	global_load_lds_dwordx4 v196, s[100:101]
	ds_read_b128 v[180:183], v238 offset:54272
	ds_read_b128 v[184:187], v238 offset:55296
	ds_read_b128 v[188:191], v238 offset:56320
	s_waitcnt vmcnt(8)
	s_waitcnt lgkmcnt(0)
	s_barrier
	v_mfma_f32_16x16x32_bf16 v[60:63], v[128:131], v[160:163], v[60:63]
	v_mfma_f32_16x16x32_bf16 v[56:59], v[136:139], v[160:163], v[56:59]
	v_mfma_f32_16x16x32_bf16 v[44:47], v[128:131], v[168:171], v[44:47]
	v_mfma_f32_16x16x32_bf16 v[40:43], v[136:139], v[168:171], v[40:43]
	v_mfma_f32_16x16x32_bf16 v[28:31], v[128:131], v[176:179], v[28:31]
	v_mfma_f32_16x16x32_bf16 v[24:27], v[136:139], v[176:179], v[24:27]
	v_mfma_f32_16x16x32_bf16 v[12:15], v[128:131], v[184:187], v[12:15]
	v_mfma_f32_16x16x32_bf16 v[8:11], v[136:139], v[184:187], v[8:11]
	v_mfma_f32_16x16x32_bf16 v[60:63], v[132:135], v[164:167], v[60:63]
	v_mfma_f32_16x16x32_bf16 v[56:59], v[140:143], v[164:167], v[56:59]
	v_mfma_f32_16x16x32_bf16 v[44:47], v[132:135], v[172:175], v[44:47]
	v_mfma_f32_16x16x32_bf16 v[40:43], v[140:143], v[172:175], v[40:43]
	v_mfma_f32_16x16x32_bf16 v[28:31], v[132:135], v[180:183], v[28:31]
	v_mfma_f32_16x16x32_bf16 v[24:27], v[140:143], v[180:183], v[24:27]
	v_mfma_f32_16x16x32_bf16 v[12:15], v[132:135], v[188:191], v[12:15]
	v_mfma_f32_16x16x32_bf16 v[8:11], v[140:143], v[188:191], v[8:11]
	v_mfma_f32_16x16x32_bf16 v[52:55], v[144:147], v[160:163], v[52:55]
	v_mfma_f32_16x16x32_bf16 v[48:51], v[152:155], v[160:163], v[48:51]
	v_mfma_f32_16x16x32_bf16 v[36:39], v[144:147], v[168:171], v[36:39]
	v_mfma_f32_16x16x32_bf16 v[32:35], v[152:155], v[168:171], v[32:35]
	v_mfma_f32_16x16x32_bf16 v[20:23], v[144:147], v[176:179], v[20:23]
	v_mfma_f32_16x16x32_bf16 v[16:19], v[152:155], v[176:179], v[16:19]
	v_mfma_f32_16x16x32_bf16 v[4:7], v[144:147], v[184:187], v[4:7]
	v_mfma_f32_16x16x32_bf16 v[0:3], v[152:155], v[184:187], v[0:3]
	v_mfma_f32_16x16x32_bf16 v[52:55], v[148:151], v[164:167], v[52:55]
	v_mfma_f32_16x16x32_bf16 v[48:51], v[156:159], v[164:167], v[48:51]
	v_mfma_f32_16x16x32_bf16 v[36:39], v[148:151], v[172:175], v[36:39]
	v_mfma_f32_16x16x32_bf16 v[32:35], v[156:159], v[172:175], v[32:35]
	v_mfma_f32_16x16x32_bf16 v[20:23], v[148:151], v[180:183], v[20:23]
	v_mfma_f32_16x16x32_bf16 v[16:19], v[156:159], v[180:183], v[16:19]
	v_mfma_f32_16x16x32_bf16 v[4:7], v[148:151], v[188:191], v[4:7]
	v_mfma_f32_16x16x32_bf16 v[0:3], v[156:159], v[188:191], v[0:3]
	s_barrier
	s_add_i32 s76, s76, 2
	s_add_u32 s12, s12, 0x100
	s_addc_u32 s75, s75, 0
	s_mov_b64 s[48:49], s[6:7]
	v_readlane_b32 s98, v248, 0
	s_nop 3
	s_cmp_ge_u32 s98, 0x100
	s_cbranch_scc1 .Lgprio_skip_1
	s_setprio 1

; #define PG8_STAGE(bufoff, gbase, voff) do { _Pragma("unroll") for (int _i = 0; _i < 2; ++_i) \
;         __builtin_amdgcn_global_load_lds((const unsigned*)((const char*)(gbase) + (voff)[_i]), (PG8_LAS unsigned*)(lds + (bufoff) + ldsw + _i * 8192), 16, 0, 0); } while (0)
; #define PG8_LDA(dst, b, h) do { _Pragma("unroll") for (int m = 0; m < 4; ++m) _Pragma("unroll") for (int k = 0; k < 2; ++k) dst[m][k] = *(const PG8_LAS bf16x8*)(lds + PG8_SA(b, h) + aoff + m * 2048 + k * 1024); } while (0)
; #define PG8_LDB(dst, b, h) do { _Pragma("unroll") for (int n = 0; n < 2; ++n) _Pragma("unroll") for (int k = 0; k < 2; ++k) dst[n][k] = *(const PG8_LAS bf16x8*)(lds + PG8_SB(b, h) + boff + n * 2048 + k * 1024); } while (0)
; #define PG8_WAIT_V(n) asm volatile("s_waitcnt vmcnt(" #n ")" ::: "memory")
; #define PG8_WAIT_L(n) asm volatile("s_waitcnt lgkmcnt(" #n ")" ::: "memory")
; #define PG8_BAR __builtin_amdgcn_s_barrier()
; template <class Epi, class Sched, bool ALIGN_EPI = false, bool SP2 = false>
; __device__ __forceinline__ void gemm_phase(PG8_LAS unsigned char* lds, const Gemm g, const Sched& S, const Epi& E, int tid_in) {
;     ...
;         const char* nA = has_next ? (const char*)g.A + (size_t)nxt.pm * tstep : cA; const char* nB = has_next ? (const char*)g.Bt + (size_t)nxt.pn * tstep : cB;
;         for (int t = 0; t < nt; t += 2) {
;             if constexpr (Epi::MIDK) { if (t == Epi::MIDK_T) { if (wr == 0) PG8_BAR; E.mid(acc, cur, wr, wc, fr, fq); if (wr == 1) PG8_BAR; } }
;             const bool last = (t == nt - 2);
;             const char* a1 = cA + (size_t)(t + 1) * kstep;
;             const char* a2 = last ? nA : cA + (size_t)(t + 2) * kstep; const char* b2 = last ? nB : cB + (size_t)(t + 2) * kstep;
;             const char* a3 = a2 + kstep; const char* b3 = b2 + kstep;
;             if (last && has_next) S.a_ready(nxt);
;             if constexpr (SP2) {
;             PG8_LDB(B0, 0, 0); PG8_LDB(B1, 0, 1); PG8_SCHED; PG8_LDA(At, 0, 0); PG8_STAGE(PG8_SA(1, 1), a1 + hstep, voffA);
;             PG8_WAIT_V(8); PG8_WAIT_L(0); PG8_BAR; PG8_MMA(0, 0, At, B0); PG8_MMA(0, 1, At, B1); PG8_BAR; PG8_SCHED;
;             PG8_LDA(At, 0, 1); PG8_STAGE(PG8_SB(0, 0), b2, voffB); PG8_STAGE(PG8_SB(0, 1), b2 + hstep, voffB); PG8_STAGE(PG8_SA(0, 0), a2, voffA);
;             PG8_WAIT_V(8); PG8_WAIT_L(0); PG8_BAR; PG8_MMA(1, 0, At, B0); PG8_MMA(1, 1, At, B1); PG8_BAR; PG8_SCHED;
.LBB0_563:
	s_ashr_i32 s35, s34, 31
	s_lshl_b64 s[0:1], s[34:35], 19
	s_add_u32 s36, s54, s0
	s_addc_u32 s37, s55, s1
	s_and_b64 s[0:1], s[4:5], exec
	s_cselect_b32 s0, s37, s47
	s_cselect_b32 s1, s36, s46
	s_ashr_i32 s31, s30, 31
	s_lshl_b64 s[38:39], s[30:31], 19
	s_add_u32 s38, s56, s38
	s_addc_u32 s39, s57, s39
	s_and_b64 s[50:51], s[4:5], exec
	s_cselect_b32 s7, s39, s49
	s_cselect_b32 s31, s38, s48
	s_add_u32 s46, s46, 0x40080
	s_addc_u32 s47, s47, 0
	s_add_u32 s35, s48, 0x100
	s_addc_u32 s45, s49, 0
	s_mov_b32 s52, -2
	s_add_u32 s48, s46, 0xfffc0080
	s_addc_u32 s49, s47, -1
	s_cmp_eq_u32 s52, 12
	s_cselect_b32 s51, s0, s49
	s_cselect_b32 s50, s1, s48
	s_cselect_b32 s49, s7, s45
	s_cselect_b32 s48, s31, s35
	s_add_i32 m0, s59, 0xc000
	ds_read_b128 v[128:131], v180
	global_load_lds_dwordx4 v158, s[46:47]
	s_add_i32 m0, s59, 0xe000
	ds_read_b128 v[132:135], v180 offset:1024
	global_load_lds_dwordx4 v160, s[46:47]
	ds_read_b128 v[136:139], v180 offset:2048
	ds_read_b128 v[140:143], v180 offset:3072
	ds_read_b128 v[166:169], v181
	ds_read_b128 v[170:173], v181 offset:1024
	ds_read_b128 v[174:177], v181 offset:2048
	ds_read_b128 v[184:187], v181 offset:3072
	ds_read_b128 v[188:191], v182
	ds_read_b128 v[192:195], v182 offset:1024
	ds_read_b128 v[196:199], v182 offset:2048
	ds_read_b128 v[200:203], v182 offset:3072
	ds_read_b128 v[204:207], v182 offset:4096
	ds_read_b128 v[208:211], v182 offset:5120
	ds_read_b128 v[212:215], v182 offset:6144
	ds_read_b128 v[216:219], v182 offset:7168
	s_waitcnt vmcnt(8)
	s_waitcnt lgkmcnt(0)
	s_barrier
	v_mfma_f32_16x16x32_bf16 v[68:71], v[128:131], v[188:191], 0
	v_mfma_f32_16x16x32_bf16 v[56:59], v[136:139], v[188:191], 0
	v_mfma_f32_16x16x32_bf16 v[52:55], v[128:131], v[196:199], 0
	v_mfma_f32_16x16x32_bf16 v[48:51], v[136:139], v[196:199], 0
	v_mfma_f32_16x16x32_bf16 v[44:47], v[128:131], v[204:207], 0
	v_mfma_f32_16x16x32_bf16 v[40:43], v[136:139], v[204:207], 0
	v_mfma_f32_16x16x32_bf16 v[36:39], v[128:131], v[212:215], 0
	v_mfma_f32_16x16x32_bf16 v[32:35], v[136:139], v[212:215], 0
	v_mfma_f32_16x16x32_bf16 v[68:71], v[132:135], v[192:195], v[68:71]
	v_mfma_f32_16x16x32_bf16 v[56:59], v[140:143], v[192:195], v[56:59]
	v_mfma_f32_16x16x32_bf16 v[52:55], v[132:135], v[200:203], v[52:55]
	v_mfma_f32_16x16x32_bf16 v[48:51], v[140:143], v[200:203], v[48:51]
	v_mfma_f32_16x16x32_bf16 v[44:47], v[132:135], v[208:211], v[44:47]
	v_mfma_f32_16x16x32_bf16 v[40:43], v[140:143], v[208:211], v[40:43]
	v_mfma_f32_16x16x32_bf16 v[36:39], v[132:135], v[216:219], v[36:39]
	v_mfma_f32_16x16x32_bf16 v[32:35], v[140:143], v[216:219], v[32:35]
	v_mfma_f32_16x16x32_bf16 v[124:127], v[166:169], v[188:191], 0
	v_mfma_f32_16x16x32_bf16 v[120:123], v[174:177], v[188:191], 0
	v_mfma_f32_16x16x32_bf16 v[116:119], v[166:169], v[196:199], 0
	v_mfma_f32_16x16x32_bf16 v[112:115], v[174:177], v[196:199], 0
	v_mfma_f32_16x16x32_bf16 v[108:111], v[166:169], v[204:207], 0
	v_mfma_f32_16x16x32_bf16 v[104:107], v[174:177], v[204:207], 0
	v_mfma_f32_16x16x32_bf16 v[100:103], v[166:169], v[212:215], 0
	v_mfma_f32_16x16x32_bf16 v[96:99], v[174:177], v[212:215], 0
	v_mfma_f32_16x16x32_bf16 v[124:127], v[170:173], v[192:195], v[124:127]
	v_mfma_f32_16x16x32_bf16 v[120:123], v[184:187], v[192:195], v[120:123]
	v_mfma_f32_16x16x32_bf16 v[116:119], v[170:173], v[200:203], v[116:119]
	v_mfma_f32_16x16x32_bf16 v[112:115], v[184:187], v[200:203], v[112:115]
	v_mfma_f32_16x16x32_bf16 v[108:111], v[170:173], v[208:211], v[108:111]
	v_mfma_f32_16x16x32_bf16 v[104:107], v[184:187], v[208:211], v[104:107]
	v_mfma_f32_16x16x32_bf16 v[100:103], v[170:173], v[216:219], v[100:103]
	v_mfma_f32_16x16x32_bf16 v[96:99], v[184:187], v[216:219], v[96:99]
	s_barrier
	s_add_u32 s98, s48, s14
	s_addc_u32 s99, s49, s15
	s_add_u32 s100, s50, s14
	s_addc_u32 s101, s51, s15
	s_add_i32 s53, s77, s29
	s_mov_b32 m0, s53
	ds_read_b128 v[188:191], v182 offset:16384
	global_load_lds_dwordx4 v146, s[48:49]
	s_add_i32 m0, s53, 0x2000
	s_add_u32 s88, s48, 0x40000
	s_addc_u32 s89, s49, 0
	s_add_i32 s53, s78, s29
	global_load_lds_dwordx4 v150, s[48:49]
	s_mov_b32 m0, s53
	ds_read_b128 v[192:195], v182 offset:17408
	global_load_lds_dwordx4 v146, s[88:89]
	s_add_i32 m0, s53, 0x2000
	ds_read_b128 v[196:199], v182 offset:18432
	global_load_lds_dwordx4 v150, s[88:89]
	s_mov_b32 m0, s59
	ds_read_b128 v[200:203], v182 offset:19456
	global_load_lds_dwordx4 v144, s[50:51]
	s_mov_b32 m0, s60
	ds_read_b128 v[204:207], v182 offset:20480
	global_load_lds_dwordx4 v148, s[50:51]
	ds_read_b128 v[208:211], v182 offset:21504
	ds_read_b128 v[212:215], v182 offset:22528
	ds_read_b128 v[216:219], v182 offset:23552
	s_waitcnt vmcnt(8)
	s_waitcnt lgkmcnt(0)
	s_barrier
; #define PG8_STAGE(bufoff, gbase, voff) do { _Pragma("unroll") for (int _i = 0; _i < 2; ++_i) \
;         __builtin_amdgcn_global_load_lds((const unsigned*)((const char*)(gbase) + (voff)[_i]), (PG8_LAS unsigned*)(lds + (bufoff) + ldsw + _i * 8192), 16, 0, 0); } while (0)
; #define PG8_LDA(dst, b, h) do { _Pragma("unroll") for (int m = 0; m < 4; ++m) _Pragma("unroll") for (int k = 0; k < 2; ++k) dst[m][k] = *(const PG8_LAS bf16x8*)(lds + PG8_SA(b, h) + aoff + m * 2048 + k * 1024); } while (0)
; #define PG8_LDB(dst, b, h) do { _Pragma("unroll") for (int n = 0; n < 2; ++n) _Pragma("unroll") for (int k = 0; k < 2; ++k) dst[n][k] = *(const PG8_LAS bf16x8*)(lds + PG8_SB(b, h) + boff + n * 2048 + k * 1024); } while (0)
; #define PG8_MMA(ai, bj, At, Bt) do { __builtin_amdgcn_s_setprio(1); _Pragma("unroll") for (int m = 0; m < 4; ++m) _Pragma("unroll") for (int n = 0; n < 2; ++n) _Pragma("unroll") for (int k = 0; k < 2; ++k) \
;         acc[ai][bj][m][n] = __builtin_amdgcn_mfma_f32_16x16x32_bf16(Bt[n][k], At[m][k], acc[ai][bj][m][n], 0, 0, 0); __builtin_amdgcn_s_setprio(0); } while (0)
; #define PG8_WAIT_V(n) asm volatile("s_waitcnt vmcnt(" #n ")" ::: "memory")
; #define PG8_WAIT_L(n) asm volatile("s_waitcnt lgkmcnt(" #n ")" ::: "memory")
; #define PG8_BAR __builtin_amdgcn_s_barrier()
; #define PG8_SCHED __builtin_amdgcn_sched_barrier(0)
; template <class Epi, class Sched, bool ALIGN_EPI = false, bool SP2 = false>
; __device__ __forceinline__ void gemm_phase(PG8_LAS unsigned char* lds, const Gemm g, const Sched& S, const Epi& E, int tid_in) {
;     ...
;             PG8_WAIT_V(8); PG8_WAIT_L(0); PG8_BAR; PG8_MMA(1, 0, At, B0); PG8_MMA(1, 1, At, B1); PG8_BAR; PG8_SCHED;
;             PG8_LDB(B0, 1, 0); PG8_LDB(B1, 1, 1); PG8_SCHED; PG8_LDA(At, 1, 0); PG8_STAGE(PG8_SA(0, 1), a2 + hstep, voffA);
;             PG8_WAIT_V(8); PG8_WAIT_L(0); PG8_BAR; PG8_MMA(0, 0, At, B0); PG8_MMA(0, 1, At, B1); PG8_BAR; PG8_SCHED;
	v_mfma_f32_16x16x32_bf16 v[28:31], v[128:131], v[188:191], 0
	v_mfma_f32_16x16x32_bf16 v[24:27], v[136:139], v[188:191], 0
	v_mfma_f32_16x16x32_bf16 v[20:23], v[128:131], v[196:199], 0
	v_mfma_f32_16x16x32_bf16 v[16:19], v[136:139], v[196:199], 0
	v_mfma_f32_16x16x32_bf16 v[12:15], v[128:131], v[204:207], 0
	v_mfma_f32_16x16x32_bf16 v[8:11], v[136:139], v[204:207], 0
	v_mfma_f32_16x16x32_bf16 v[4:7], v[128:131], v[212:215], 0
	v_mfma_f32_16x16x32_bf16 v[0:3], v[136:139], v[212:215], 0
	v_mfma_f32_16x16x32_bf16 v[28:31], v[132:135], v[192:195], v[28:31]
	v_mfma_f32_16x16x32_bf16 v[24:27], v[140:143], v[192:195], v[24:27]
	v_mfma_f32_16x16x32_bf16 v[20:23], v[132:135], v[200:203], v[20:23]
	v_mfma_f32_16x16x32_bf16 v[16:19], v[140:143], v[200:203], v[16:19]
	v_mfma_f32_16x16x32_bf16 v[12:15], v[132:135], v[208:211], v[12:15]
	v_mfma_f32_16x16x32_bf16 v[8:11], v[140:143], v[208:211], v[8:11]
	v_mfma_f32_16x16x32_bf16 v[4:7], v[132:135], v[216:219], v[4:7]
	v_mfma_f32_16x16x32_bf16 v[0:3], v[140:143], v[216:219], v[0:3]
	v_mfma_f32_16x16x32_bf16 v[92:95], v[166:169], v[188:191], 0
	v_mfma_f32_16x16x32_bf16 v[88:91], v[174:177], v[188:191], 0
	v_mfma_f32_16x16x32_bf16 v[84:87], v[166:169], v[196:199], 0
	v_mfma_f32_16x16x32_bf16 v[80:83], v[174:177], v[196:199], 0
	v_mfma_f32_16x16x32_bf16 v[76:79], v[166:169], v[204:207], 0
	v_mfma_f32_16x16x32_bf16 v[72:75], v[174:177], v[204:207], 0
	v_mfma_f32_16x16x32_bf16 v[64:67], v[166:169], v[212:215], 0
	v_mfma_f32_16x16x32_bf16 v[60:63], v[174:177], v[212:215], 0
	v_mfma_f32_16x16x32_bf16 v[92:95], v[170:173], v[192:195], v[92:95]
	v_mfma_f32_16x16x32_bf16 v[88:91], v[184:187], v[192:195], v[88:91]
	v_mfma_f32_16x16x32_bf16 v[84:87], v[170:173], v[200:203], v[84:87]
	v_mfma_f32_16x16x32_bf16 v[80:83], v[184:187], v[200:203], v[80:83]
	v_mfma_f32_16x16x32_bf16 v[76:79], v[170:173], v[208:211], v[76:79]
	v_mfma_f32_16x16x32_bf16 v[72:75], v[184:187], v[208:211], v[72:75]
	v_mfma_f32_16x16x32_bf16 v[64:67], v[170:173], v[216:219], v[64:67]
	v_mfma_f32_16x16x32_bf16 v[60:63], v[184:187], v[216:219], v[60:63]
	s_barrier
	s_add_i32 s53, 0, 0x18000
	s_add_i32 s88, 0, 0x1c000
	s_add_u32 s50, s50, 0x40000
	s_addc_u32 s51, s51, 0
	s_mov_b32 m0, s61
	s_nop 0
	global_load_lds_dwordx4 v144, s[50:51]
	s_mov_b32 m0, s62
	s_nop 0
	global_load_lds_dwordx4 v148, s[50:51]
	v_add_u32_e32 v140, s53, v179
	v_add_u32_e32 v184, s88, v179
	ds_read_b128 v[128:131], v140
	ds_read_b128 v[132:135], v140 offset:1024
	ds_read_b128 v[136:139], v140 offset:2048
	ds_read_b128 v[140:143], v140 offset:3072
	ds_read_b128 v[166:169], v184
	ds_read_b128 v[170:173], v184 offset:1024
	ds_read_b128 v[174:177], v184 offset:2048
	ds_read_b128 v[184:187], v184 offset:3072
	ds_read_b128 v[188:191], v182 offset:32768
	ds_read_b128 v[192:195], v182 offset:33792
	ds_read_b128 v[196:199], v182 offset:34816
	ds_read_b128 v[200:203], v182 offset:35840
	ds_read_b128 v[204:207], v182 offset:36864
	ds_read_b128 v[208:211], v182 offset:37888
	ds_read_b128 v[212:215], v182 offset:38912
	ds_read_b128 v[216:219], v182 offset:39936
	s_waitcnt vmcnt(8)
	s_waitcnt lgkmcnt(0)
	s_barrier
	v_mfma_f32_16x16x32_bf16 v[68:71], v[128:131], v[188:191], v[68:71]
	v_mfma_f32_16x16x32_bf16 v[56:59], v[136:139], v[188:191], v[56:59]
	v_mfma_f32_16x16x32_bf16 v[52:55], v[128:131], v[196:199], v[52:55]
	v_mfma_f32_16x16x32_bf16 v[48:51], v[136:139], v[196:199], v[48:51]
	v_mfma_f32_16x16x32_bf16 v[44:47], v[128:131], v[204:207], v[44:47]
	v_mfma_f32_16x16x32_bf16 v[40:43], v[136:139], v[204:207], v[40:43]
	v_mfma_f32_16x16x32_bf16 v[36:39], v[128:131], v[212:215], v[36:39]
	v_mfma_f32_16x16x32_bf16 v[32:35], v[136:139], v[212:215], v[32:35]
	v_mfma_f32_16x16x32_bf16 v[68:71], v[132:135], v[192:195], v[68:71]
	v_mfma_f32_16x16x32_bf16 v[56:59], v[140:143], v[192:195], v[56:59]
	v_mfma_f32_16x16x32_bf16 v[52:55], v[132:135], v[200:203], v[52:55]
	v_mfma_f32_16x16x32_bf16 v[48:51], v[140:143], v[200:203], v[48:51]
	v_mfma_f32_16x16x32_bf16 v[44:47], v[132:135], v[208:211], v[44:47]
	v_mfma_f32_16x16x32_bf16 v[40:43], v[140:143], v[208:211], v[40:43]
	v_mfma_f32_16x16x32_bf16 v[36:39], v[132:135], v[216:219], v[36:39]
	v_mfma_f32_16x16x32_bf16 v[32:35], v[140:143], v[216:219], v[32:35]
	v_mfma_f32_16x16x32_bf16 v[124:127], v[166:169], v[188:191], v[124:127]
	v_mfma_f32_16x16x32_bf16 v[120:123], v[174:177], v[188:191], v[120:123]
	v_mfma_f32_16x16x32_bf16 v[116:119], v[166:169], v[196:199], v[116:119]
	v_mfma_f32_16x16x32_bf16 v[112:115], v[174:177], v[196:199], v[112:115]
	v_mfma_f32_16x16x32_bf16 v[108:111], v[166:169], v[204:207], v[108:111]
	v_mfma_f32_16x16x32_bf16 v[104:107], v[174:177], v[204:207], v[104:107]
	v_mfma_f32_16x16x32_bf16 v[100:103], v[166:169], v[212:215], v[100:103]
	v_mfma_f32_16x16x32_bf16 v[96:99], v[174:177], v[212:215], v[96:99]
	v_mfma_f32_16x16x32_bf16 v[124:127], v[170:173], v[192:195], v[124:127]
	v_mfma_f32_16x16x32_bf16 v[120:123], v[184:187], v[192:195], v[120:123]
	v_mfma_f32_16x16x32_bf16 v[116:119], v[170:173], v[200:203], v[116:119]
	v_mfma_f32_16x16x32_bf16 v[112:115], v[184:187], v[200:203], v[112:115]
	v_mfma_f32_16x16x32_bf16 v[108:111], v[170:173], v[208:211], v[108:111]
	v_mfma_f32_16x16x32_bf16 v[104:107], v[184:187], v[208:211], v[104:107]
	v_mfma_f32_16x16x32_bf16 v[100:103], v[170:173], v[216:219], v[100:103]
	v_mfma_f32_16x16x32_bf16 v[96:99], v[184:187], v[216:219], v[96:99]
	s_barrier
; #define PG8_STAGE(bufoff, gbase, voff) do { _Pragma("unroll") for (int _i = 0; _i < 2; ++_i) \
;         __builtin_amdgcn_global_load_lds((const unsigned*)((const char*)(gbase) + (voff)[_i]), (PG8_LAS unsigned*)(lds + (bufoff) + ldsw + _i * 8192), 16, 0, 0); } while (0)
; #define PG8_LDA(dst, b, h) do { _Pragma("unroll") for (int m = 0; m < 4; ++m) _Pragma("unroll") for (int k = 0; k < 2; ++k) dst[m][k] = *(const PG8_LAS bf16x8*)(lds + PG8_SA(b, h) + aoff + m * 2048 + k * 1024); } while (0)
; #define PG8_MMA(ai, bj, At, Bt) do { __builtin_amdgcn_s_setprio(1); _Pragma("unroll") for (int m = 0; m < 4; ++m) _Pragma("unroll") for (int n = 0; n < 2; ++n) _Pragma("unroll") for (int k = 0; k < 2; ++k) \
;         acc[ai][bj][m][n] = __builtin_amdgcn_mfma_f32_16x16x32_bf16(Bt[n][k], At[m][k], acc[ai][bj][m][n], 0, 0, 0); __builtin_amdgcn_s_setprio(0); } while (0)
; #define PG8_WAIT_V(n) asm volatile("s_waitcnt vmcnt(" #n ")" ::: "memory")
; #define PG8_WAIT_L(n) asm volatile("s_waitcnt lgkmcnt(" #n ")" ::: "memory")
; #define PG8_BAR __builtin_amdgcn_s_barrier()
; #define PG8_SCHED __builtin_amdgcn_sched_barrier(0)
; template <class Epi, class Sched, bool ALIGN_EPI = false, bool SP2 = false>
; __device__ __forceinline__ void gemm_phase(PG8_LAS unsigned char* lds, const Gemm g, const Sched& S, const Epi& E, int tid_in) {
;     ...
;             PG8_LDA(At, 1, 1); PG8_STAGE(PG8_SB(1, 0), b3, voffB); PG8_STAGE(PG8_SB(1, 1), b3 + hstep, voffB); PG8_STAGE(PG8_SA(1, 0), a3, voffA);
;             PG8_WAIT_V(8); PG8_WAIT_L(0); PG8_BAR; PG8_MMA(1, 0, At, B0); PG8_MMA(1, 1, At, B1); PG8_BAR; PG8_SCHED;
	s_add_i32 s50, s53, s29
	s_mov_b32 m0, s50
	ds_read_b128 v[188:191], v182 offset:49152
	global_load_lds_dwordx4 v146, s[98:99]
	s_add_i32 m0, s50, 0x2000
	s_add_u32 s48, s48, 0x40080
	s_addc_u32 s49, s49, 0
	s_add_i32 s50, s88, s29
	global_load_lds_dwordx4 v150, s[98:99]
	s_mov_b32 m0, s50
	ds_read_b128 v[192:195], v182 offset:50176
	global_load_lds_dwordx4 v146, s[48:49]
	s_add_i32 m0, s50, 0x2000
	ds_read_b128 v[196:199], v182 offset:51200
	global_load_lds_dwordx4 v150, s[48:49]
	s_mov_b32 m0, s63
	ds_read_b128 v[200:203], v182 offset:52224
	global_load_lds_dwordx4 v144, s[100:101]
	s_mov_b32 m0, s64
	ds_read_b128 v[204:207], v182 offset:53248
	global_load_lds_dwordx4 v148, s[100:101]
	ds_read_b128 v[208:211], v182 offset:54272
	ds_read_b128 v[212:215], v182 offset:55296
	ds_read_b128 v[216:219], v182 offset:56320
	s_waitcnt vmcnt(8)
	s_waitcnt lgkmcnt(0)
	s_barrier
	v_mfma_f32_16x16x32_bf16 v[28:31], v[128:131], v[188:191], v[28:31]
	v_mfma_f32_16x16x32_bf16 v[24:27], v[136:139], v[188:191], v[24:27]
	v_mfma_f32_16x16x32_bf16 v[20:23], v[128:131], v[196:199], v[20:23]
	v_mfma_f32_16x16x32_bf16 v[16:19], v[136:139], v[196:199], v[16:19]
	v_mfma_f32_16x16x32_bf16 v[12:15], v[128:131], v[204:207], v[12:15]
	v_mfma_f32_16x16x32_bf16 v[8:11], v[136:139], v[204:207], v[8:11]
	v_mfma_f32_16x16x32_bf16 v[4:7], v[128:131], v[212:215], v[4:7]
	v_mfma_f32_16x16x32_bf16 v[0:3], v[136:139], v[212:215], v[0:3]
	v_mfma_f32_16x16x32_bf16 v[28:31], v[132:135], v[192:195], v[28:31]
	v_mfma_f32_16x16x32_bf16 v[24:27], v[140:143], v[192:195], v[24:27]
	v_mfma_f32_16x16x32_bf16 v[20:23], v[132:135], v[200:203], v[20:23]
	v_mfma_f32_16x16x32_bf16 v[16:19], v[140:143], v[200:203], v[16:19]
	v_mfma_f32_16x16x32_bf16 v[12:15], v[132:135], v[208:211], v[12:15]
	v_mfma_f32_16x16x32_bf16 v[8:11], v[140:143], v[208:211], v[8:11]
	v_mfma_f32_16x16x32_bf16 v[4:7], v[132:135], v[216:219], v[4:7]
	v_mfma_f32_16x16x32_bf16 v[0:3], v[140:143], v[216:219], v[0:3]
	v_mfma_f32_16x16x32_bf16 v[92:95], v[166:169], v[188:191], v[92:95]
	v_mfma_f32_16x16x32_bf16 v[88:91], v[174:177], v[188:191], v[88:91]
	v_mfma_f32_16x16x32_bf16 v[84:87], v[166:169], v[196:199], v[84:87]
	v_mfma_f32_16x16x32_bf16 v[80:83], v[174:177], v[196:199], v[80:83]
	v_mfma_f32_16x16x32_bf16 v[76:79], v[166:169], v[204:207], v[76:79]
	v_mfma_f32_16x16x32_bf16 v[72:75], v[174:177], v[204:207], v[72:75]
	v_mfma_f32_16x16x32_bf16 v[64:67], v[166:169], v[212:215], v[64:67]
	v_mfma_f32_16x16x32_bf16 v[60:63], v[174:177], v[212:215], v[60:63]
	v_mfma_f32_16x16x32_bf16 v[92:95], v[170:173], v[192:195], v[92:95]
	v_mfma_f32_16x16x32_bf16 v[88:91], v[184:187], v[192:195], v[88:91]
	v_mfma_f32_16x16x32_bf16 v[84:87], v[170:173], v[200:203], v[84:87]
	v_mfma_f32_16x16x32_bf16 v[80:83], v[184:187], v[200:203], v[80:83]
	v_mfma_f32_16x16x32_bf16 v[76:79], v[170:173], v[208:211], v[76:79]
	v_mfma_f32_16x16x32_bf16 v[72:75], v[184:187], v[208:211], v[72:75]
	v_mfma_f32_16x16x32_bf16 v[64:67], v[170:173], v[216:219], v[64:67]
	v_mfma_f32_16x16x32_bf16 v[60:63], v[184:187], v[216:219], v[60:63]
	s_barrier
	s_add_i32 s52, s52, 2
	s_add_u32 s46, s46, 0x100
	s_addc_u32 s47, s47, 0
	s_add_u32 s35, s35, 0x100
	s_addc_u32 s45, s45, 0
	v_readlane_b32 s98, v248, 0
	s_nop 3
	s_cmp_ge_u32 s98, 0x100
	s_cbranch_scc1 .Lgprio_skip_2
	s_setprio 1

; #define PG8_STAGE(bufoff, gbase, voff) do { _Pragma("unroll") for (int _i = 0; _i < 2; ++_i) \
;         __builtin_amdgcn_global_load_lds((const unsigned*)((const char*)(gbase) + (voff)[_i]), (PG8_LAS unsigned*)(lds + (bufoff) + ldsw + _i * 8192), 16, 0, 0); } while (0)
; #define PG8_LDA(dst, b, h) do { _Pragma("unroll") for (int m = 0; m < 4; ++m) _Pragma("unroll") for (int k = 0; k < 2; ++k) dst[m][k] = *(const PG8_LAS bf16x8*)(lds + PG8_SA(b, h) + aoff + m * 2048 + k * 1024); } while (0)
; #define PG8_LDB(dst, b, h) do { _Pragma("unroll") for (int n = 0; n < 2; ++n) _Pragma("unroll") for (int k = 0; k < 2; ++k) dst[n][k] = *(const PG8_LAS bf16x8*)(lds + PG8_SB(b, h) + boff + n * 2048 + k * 1024); } while (0)
; #define PG8_WAIT_V(n) asm volatile("s_waitcnt vmcnt(" #n ")" ::: "memory")
; #define PG8_WAIT_L(n) asm volatile("s_waitcnt lgkmcnt(" #n ")" ::: "memory")
; #define PG8_BAR __builtin_amdgcn_s_barrier()
; template <class Epi, class Sched, bool ALIGN_EPI = false, bool SP2 = false>
; __device__ __forceinline__ void gemm_phase(PG8_LAS unsigned char* lds, const Gemm g, const Sched& S, const Epi& E, int tid_in) {
;     ...
;         const char* nA = has_next ? (const char*)g.A + (size_t)nxt.pm * tstep : cA; const char* nB = has_next ? (const char*)g.Bt + (size_t)nxt.pn * tstep : cB;
;         for (int t = 0; t < nt; t += 2) {
;             if constexpr (Epi::MIDK) { if (t == Epi::MIDK_T) { if (wr == 0) PG8_BAR; E.mid(acc, cur, wr, wc, fr, fq); if (wr == 1) PG8_BAR; } }
;             const bool last = (t == nt - 2);
;             const char* a1 = cA + (size_t)(t + 1) * kstep;
;             const char* a2 = last ? nA : cA + (size_t)(t + 2) * kstep; const char* b2 = last ? nB : cB + (size_t)(t + 2) * kstep;
;             const char* a3 = a2 + kstep; const char* b3 = b2 + kstep;
;             if (last && has_next) S.a_ready(nxt);
;             if constexpr (SP2) {
;             PG8_LDB(B0, 0, 0); PG8_LDB(B1, 0, 1); PG8_SCHED; PG8_LDA(At, 0, 0); PG8_STAGE(PG8_SA(1, 1), a1 + hstep, voffA);
;             PG8_WAIT_V(8); PG8_WAIT_L(0); PG8_BAR; PG8_MMA(0, 0, At, B0); PG8_MMA(0, 1, At, B1); PG8_BAR; PG8_SCHED;
;             PG8_LDA(At, 0, 1); PG8_STAGE(PG8_SB(0, 0), b2, voffB); PG8_STAGE(PG8_SB(0, 1), b2 + hstep, voffB); PG8_STAGE(PG8_SA(0, 0), a2, voffA);
;             PG8_WAIT_V(8); PG8_WAIT_L(0); PG8_BAR; PG8_MMA(1, 0, At, B0); PG8_MMA(1, 1, At, B1); PG8_BAR; PG8_SCHED;
.LBB0_1147:
	s_ashr_i32 s23, s22, 31
	s_lshl_b64 s[24:25], s[22:23], 19
	s_add_u32 s24, s38, s24
	s_addc_u32 s25, s39, s25
	s_and_b64 s[26:27], s[4:5], exec
	s_cselect_b32 s23, s25, s31
	s_cselect_b32 s29, s24, s30
	s_ashr_i32 s21, s20, 31
	s_lshl_b64 s[26:27], s[20:21], 19
	s_add_u32 s26, s44, s26
	s_addc_u32 s27, s45, s27
	s_and_b64 s[36:37], s[4:5], exec
	s_cselect_b32 s21, s27, s35
	s_cselect_b32 s57, s26, s34
	s_add_u32 s30, s30, 0x40080
	s_addc_u32 s31, s31, 0
	s_add_u32 s58, s34, 0x100
	s_addc_u32 s59, s35, 0
	s_mov_b32 s60, -2
	s_waitcnt lgkmcnt(0)
	s_add_u32 s34, s30, 0xfffc0080
	s_addc_u32 s35, s31, -1
	s_cmp_eq_u32 s60, 12
	s_cselect_b32 s37, s23, s35
	s_cselect_b32 s36, s29, s34
	s_cselect_b32 s35, s21, s59
	s_cselect_b32 s34, s57, s58
	s_add_i32 m0, s1, 0xc000
	ds_read_b128 v[128:131], v191
	global_load_lds_dwordx4 v160, s[30:31]
	s_add_i32 m0, s1, 0xe000
	ds_read_b128 v[132:135], v191 offset:1024
	global_load_lds_dwordx4 v162, s[30:31]
	ds_read_b128 v[136:139], v191 offset:2048
	ds_read_b128 v[140:143], v191 offset:3072
	ds_read_b128 v[144:147], v192
	ds_read_b128 v[148:151], v192 offset:1024
	ds_read_b128 v[168:171], v192 offset:2048
	ds_read_b128 v[172:175], v192 offset:3072
	ds_read_b128 v[176:179], v193
	ds_read_b128 v[180:183], v193 offset:1024
	ds_read_b128 v[194:197], v193 offset:2048
	ds_read_b128 v[198:201], v193 offset:3072
	ds_read_b128 v[202:205], v193 offset:4096
	ds_read_b128 v[206:209], v193 offset:5120
	ds_read_b128 v[210:213], v193 offset:6144
	ds_read_b128 v[214:217], v193 offset:7168
	s_waitcnt vmcnt(8)
	s_waitcnt lgkmcnt(0)
	s_barrier
	v_mfma_f32_16x16x32_bf16 v[124:127], v[128:131], v[176:179], 0
	v_mfma_f32_16x16x32_bf16 v[120:123], v[136:139], v[176:179], 0
	v_mfma_f32_16x16x32_bf16 v[108:111], v[128:131], v[194:197], 0
	v_mfma_f32_16x16x32_bf16 v[104:107], v[136:139], v[194:197], 0
	v_mfma_f32_16x16x32_bf16 v[92:95], v[128:131], v[202:205], 0
	v_mfma_f32_16x16x32_bf16 v[88:91], v[136:139], v[202:205], 0
	v_mfma_f32_16x16x32_bf16 v[76:79], v[128:131], v[210:213], 0
	v_mfma_f32_16x16x32_bf16 v[72:75], v[136:139], v[210:213], 0
	v_mfma_f32_16x16x32_bf16 v[124:127], v[132:135], v[180:183], v[124:127]
	v_mfma_f32_16x16x32_bf16 v[120:123], v[140:143], v[180:183], v[120:123]
	v_mfma_f32_16x16x32_bf16 v[108:111], v[132:135], v[198:201], v[108:111]
	v_mfma_f32_16x16x32_bf16 v[104:107], v[140:143], v[198:201], v[104:107]
	v_mfma_f32_16x16x32_bf16 v[92:95], v[132:135], v[206:209], v[92:95]
	v_mfma_f32_16x16x32_bf16 v[88:91], v[140:143], v[206:209], v[88:91]
	v_mfma_f32_16x16x32_bf16 v[76:79], v[132:135], v[214:217], v[76:79]
	v_mfma_f32_16x16x32_bf16 v[72:75], v[140:143], v[214:217], v[72:75]
	v_mfma_f32_16x16x32_bf16 v[116:119], v[144:147], v[176:179], 0
	v_mfma_f32_16x16x32_bf16 v[112:115], v[168:171], v[176:179], 0
	v_mfma_f32_16x16x32_bf16 v[100:103], v[144:147], v[194:197], 0
	v_mfma_f32_16x16x32_bf16 v[96:99], v[168:171], v[194:197], 0
	v_mfma_f32_16x16x32_bf16 v[84:87], v[144:147], v[202:205], 0
	v_mfma_f32_16x16x32_bf16 v[80:83], v[168:171], v[202:205], 0
	v_mfma_f32_16x16x32_bf16 v[68:71], v[144:147], v[210:213], 0
	v_mfma_f32_16x16x32_bf16 v[64:67], v[168:171], v[210:213], 0
	v_mfma_f32_16x16x32_bf16 v[116:119], v[148:151], v[180:183], v[116:119]
	v_mfma_f32_16x16x32_bf16 v[112:115], v[172:175], v[180:183], v[112:115]
	v_mfma_f32_16x16x32_bf16 v[100:103], v[148:151], v[198:201], v[100:103]
	v_mfma_f32_16x16x32_bf16 v[96:99], v[172:175], v[198:201], v[96:99]
	v_mfma_f32_16x16x32_bf16 v[84:87], v[148:151], v[206:209], v[84:87]
	v_mfma_f32_16x16x32_bf16 v[80:83], v[172:175], v[206:209], v[80:83]
	v_mfma_f32_16x16x32_bf16 v[68:71], v[148:151], v[214:217], v[68:71]
	v_mfma_f32_16x16x32_bf16 v[64:67], v[172:175], v[214:217], v[64:67]
	s_barrier
	s_add_u32 s98, s34, s16
	s_addc_u32 s99, s35, s17
	s_add_u32 s100, s36, s16
	s_addc_u32 s101, s37, s17
	s_add_i32 s61, s54, s0
	s_mov_b32 m0, s61
	ds_read_b128 v[176:179], v193 offset:16384
	global_load_lds_dwordx4 v154, s[34:35]
	s_add_i32 m0, s61, 0x2000
	s_add_u32 s62, s34, 0x40000
	s_addc_u32 s63, s35, 0
	s_add_i32 s61, s55, s0
	global_load_lds_dwordx4 v158, s[34:35]
	s_mov_b32 m0, s61
	ds_read_b128 v[180:183], v193 offset:17408
	global_load_lds_dwordx4 v154, s[62:63]
	s_add_i32 m0, s61, 0x2000
	ds_read_b128 v[194:197], v193 offset:18432
	global_load_lds_dwordx4 v158, s[62:63]
	s_mov_b32 m0, s1
	ds_read_b128 v[198:201], v193 offset:19456
	global_load_lds_dwordx4 v152, s[36:37]
	s_mov_b32 m0, s46
	ds_read_b128 v[202:205], v193 offset:20480
	global_load_lds_dwordx4 v156, s[36:37]
	ds_read_b128 v[206:209], v193 offset:21504
	ds_read_b128 v[210:213], v193 offset:22528
	ds_read_b128 v[214:217], v193 offset:23552
	s_waitcnt vmcnt(8)
	s_waitcnt lgkmcnt(0)
	s_barrier
; #define PG8_STAGE(bufoff, gbase, voff) do { _Pragma("unroll") for (int _i = 0; _i < 2; ++_i) \
;         __builtin_amdgcn_global_load_lds((const unsigned*)((const char*)(gbase) + (voff)[_i]), (PG8_LAS unsigned*)(lds + (bufoff) + ldsw + _i * 8192), 16, 0, 0); } while (0)
; #define PG8_LDA(dst, b, h) do { _Pragma("unroll") for (int m = 0; m < 4; ++m) _Pragma("unroll") for (int k = 0; k < 2; ++k) dst[m][k] = *(const PG8_LAS bf16x8*)(lds + PG8_SA(b, h) + aoff + m * 2048 + k * 1024); } while (0)
; #define PG8_LDB(dst, b, h) do { _Pragma("unroll") for (int n = 0; n < 2; ++n) _Pragma("unroll") for (int k = 0; k < 2; ++k) dst[n][k] = *(const PG8_LAS bf16x8*)(lds + PG8_SB(b, h) + boff + n * 2048 + k * 1024); } while (0)
; #define PG8_MMA(ai, bj, At, Bt) do { __builtin_amdgcn_s_setprio(1); _Pragma("unroll") for (int m = 0; m < 4; ++m) _Pragma("unroll") for (int n = 0; n < 2; ++n) _Pragma("unroll") for (int k = 0; k < 2; ++k) \
;         acc[ai][bj][m][n] = __builtin_amdgcn_mfma_f32_16x16x32_bf16(Bt[n][k], At[m][k], acc[ai][bj][m][n], 0, 0, 0); __builtin_amdgcn_s_setprio(0); } while (0)
; #define PG8_WAIT_V(n) asm volatile("s_waitcnt vmcnt(" #n ")" ::: "memory")
; #define PG8_WAIT_L(n) asm volatile("s_waitcnt lgkmcnt(" #n ")" ::: "memory")
; #define PG8_BAR __builtin_amdgcn_s_barrier()
; #define PG8_SCHED __builtin_amdgcn_sched_barrier(0)
; template <class Epi, class Sched, bool ALIGN_EPI = false, bool SP2 = false>
; __device__ __forceinline__ void gemm_phase(PG8_LAS unsigned char* lds, const Gemm g, const Sched& S, const Epi& E, int tid_in) {
;     ...
;             PG8_WAIT_V(8); PG8_WAIT_L(0); PG8_BAR; PG8_MMA(1, 0, At, B0); PG8_MMA(1, 1, At, B1); PG8_BAR; PG8_SCHED;
;             PG8_LDB(B0, 1, 0); PG8_LDB(B1, 1, 1); PG8_SCHED; PG8_LDA(At, 1, 0); PG8_STAGE(PG8_SA(0, 1), a2 + hstep, voffA);
;             PG8_WAIT_V(8); PG8_WAIT_L(0); PG8_BAR; PG8_MMA(0, 0, At, B0); PG8_MMA(0, 1, At, B1); PG8_BAR; PG8_SCHED;
	v_mfma_f32_16x16x32_bf16 v[60:63], v[128:131], v[176:179], 0
	v_mfma_f32_16x16x32_bf16 v[56:59], v[136:139], v[176:179], 0
	v_mfma_f32_16x16x32_bf16 v[44:47], v[128:131], v[194:197], 0
	v_mfma_f32_16x16x32_bf16 v[40:43], v[136:139], v[194:197], 0
	v_mfma_f32_16x16x32_bf16 v[28:31], v[128:131], v[202:205], 0
	v_mfma_f32_16x16x32_bf16 v[24:27], v[136:139], v[202:205], 0
	v_mfma_f32_16x16x32_bf16 v[12:15], v[128:131], v[210:213], 0
	v_mfma_f32_16x16x32_bf16 v[8:11], v[136:139], v[210:213], 0
	v_mfma_f32_16x16x32_bf16 v[60:63], v[132:135], v[180:183], v[60:63]
	v_mfma_f32_16x16x32_bf16 v[56:59], v[140:143], v[180:183], v[56:59]
	v_mfma_f32_16x16x32_bf16 v[44:47], v[132:135], v[198:201], v[44:47]
	v_mfma_f32_16x16x32_bf16 v[40:43], v[140:143], v[198:201], v[40:43]
	v_mfma_f32_16x16x32_bf16 v[28:31], v[132:135], v[206:209], v[28:31]
	v_mfma_f32_16x16x32_bf16 v[24:27], v[140:143], v[206:209], v[24:27]
	v_mfma_f32_16x16x32_bf16 v[12:15], v[132:135], v[214:217], v[12:15]
	v_mfma_f32_16x16x32_bf16 v[8:11], v[140:143], v[214:217], v[8:11]
	v_mfma_f32_16x16x32_bf16 v[52:55], v[144:147], v[176:179], 0
	v_mfma_f32_16x16x32_bf16 v[48:51], v[168:171], v[176:179], 0
	v_mfma_f32_16x16x32_bf16 v[36:39], v[144:147], v[194:197], 0
	v_mfma_f32_16x16x32_bf16 v[32:35], v[168:171], v[194:197], 0
	v_mfma_f32_16x16x32_bf16 v[20:23], v[144:147], v[202:205], 0
	v_mfma_f32_16x16x32_bf16 v[16:19], v[168:171], v[202:205], 0
	v_mfma_f32_16x16x32_bf16 v[4:7], v[144:147], v[210:213], 0
	v_mfma_f32_16x16x32_bf16 v[0:3], v[168:171], v[210:213], 0
	v_mfma_f32_16x16x32_bf16 v[52:55], v[148:151], v[180:183], v[52:55]
	v_mfma_f32_16x16x32_bf16 v[48:51], v[172:175], v[180:183], v[48:51]
	v_mfma_f32_16x16x32_bf16 v[36:39], v[148:151], v[198:201], v[36:39]
	v_mfma_f32_16x16x32_bf16 v[32:35], v[172:175], v[198:201], v[32:35]
	v_mfma_f32_16x16x32_bf16 v[20:23], v[148:151], v[206:209], v[20:23]
	v_mfma_f32_16x16x32_bf16 v[16:19], v[172:175], v[206:209], v[16:19]
	v_mfma_f32_16x16x32_bf16 v[4:7], v[148:151], v[214:217], v[4:7]
	v_mfma_f32_16x16x32_bf16 v[0:3], v[172:175], v[214:217], v[0:3]
	s_barrier
	s_add_i32 s61, 0, 0x18000
	s_add_i32 s62, 0, 0x1c000
	s_add_u32 s36, s36, 0x40000
	s_addc_u32 s37, s37, 0
	s_mov_b32 m0, s47
	s_nop 0
	global_load_lds_dwordx4 v152, s[36:37]
	s_mov_b32 m0, s48
	s_nop 0
	global_load_lds_dwordx4 v156, s[36:37]
	v_add_u32_e32 v140, s61, v187
	v_add_u32_e32 v172, s62, v187
	ds_read_b128 v[128:131], v140
	ds_read_b128 v[132:135], v140 offset:1024
	ds_read_b128 v[136:139], v140 offset:2048
	ds_read_b128 v[140:143], v140 offset:3072
	ds_read_b128 v[144:147], v172
	ds_read_b128 v[148:151], v172 offset:1024
	ds_read_b128 v[168:171], v172 offset:2048
	ds_read_b128 v[172:175], v172 offset:3072
	ds_read_b128 v[176:179], v193 offset:32768
	ds_read_b128 v[180:183], v193 offset:33792
	ds_read_b128 v[194:197], v193 offset:34816
	ds_read_b128 v[198:201], v193 offset:35840
	ds_read_b128 v[202:205], v193 offset:36864
	ds_read_b128 v[206:209], v193 offset:37888
	ds_read_b128 v[210:213], v193 offset:38912
	ds_read_b128 v[214:217], v193 offset:39936
	s_waitcnt vmcnt(8)
	s_waitcnt lgkmcnt(0)
	s_barrier
	v_mfma_f32_16x16x32_bf16 v[124:127], v[128:131], v[176:179], v[124:127]
	v_mfma_f32_16x16x32_bf16 v[120:123], v[136:139], v[176:179], v[120:123]
	v_mfma_f32_16x16x32_bf16 v[108:111], v[128:131], v[194:197], v[108:111]
	v_mfma_f32_16x16x32_bf16 v[104:107], v[136:139], v[194:197], v[104:107]
	v_mfma_f32_16x16x32_bf16 v[92:95], v[128:131], v[202:205], v[92:95]
	v_mfma_f32_16x16x32_bf16 v[88:91], v[136:139], v[202:205], v[88:91]
	v_mfma_f32_16x16x32_bf16 v[76:79], v[128:131], v[210:213], v[76:79]
	v_mfma_f32_16x16x32_bf16 v[72:75], v[136:139], v[210:213], v[72:75]
	v_mfma_f32_16x16x32_bf16 v[124:127], v[132:135], v[180:183], v[124:127]
	v_mfma_f32_16x16x32_bf16 v[120:123], v[140:143], v[180:183], v[120:123]
	v_mfma_f32_16x16x32_bf16 v[108:111], v[132:135], v[198:201], v[108:111]
	v_mfma_f32_16x16x32_bf16 v[104:107], v[140:143], v[198:201], v[104:107]
	v_mfma_f32_16x16x32_bf16 v[92:95], v[132:135], v[206:209], v[92:95]
	v_mfma_f32_16x16x32_bf16 v[88:91], v[140:143], v[206:209], v[88:91]
	v_mfma_f32_16x16x32_bf16 v[76:79], v[132:135], v[214:217], v[76:79]
	v_mfma_f32_16x16x32_bf16 v[72:75], v[140:143], v[214:217], v[72:75]
	v_mfma_f32_16x16x32_bf16 v[116:119], v[144:147], v[176:179], v[116:119]
	v_mfma_f32_16x16x32_bf16 v[112:115], v[168:171], v[176:179], v[112:115]
	v_mfma_f32_16x16x32_bf16 v[100:103], v[144:147], v[194:197], v[100:103]
	v_mfma_f32_16x16x32_bf16 v[96:99], v[168:171], v[194:197], v[96:99]
	v_mfma_f32_16x16x32_bf16 v[84:87], v[144:147], v[202:205], v[84:87]
	v_mfma_f32_16x16x32_bf16 v[80:83], v[168:171], v[202:205], v[80:83]
	v_mfma_f32_16x16x32_bf16 v[68:71], v[144:147], v[210:213], v[68:71]
	v_mfma_f32_16x16x32_bf16 v[64:67], v[168:171], v[210:213], v[64:67]
	v_mfma_f32_16x16x32_bf16 v[116:119], v[148:151], v[180:183], v[116:119]
	v_mfma_f32_16x16x32_bf16 v[112:115], v[172:175], v[180:183], v[112:115]
	v_mfma_f32_16x16x32_bf16 v[100:103], v[148:151], v[198:201], v[100:103]
	v_mfma_f32_16x16x32_bf16 v[96:99], v[172:175], v[198:201], v[96:99]
	v_mfma_f32_16x16x32_bf16 v[84:87], v[148:151], v[206:209], v[84:87]
	v_mfma_f32_16x16x32_bf16 v[80:83], v[172:175], v[206:209], v[80:83]
	v_mfma_f32_16x16x32_bf16 v[68:71], v[148:151], v[214:217], v[68:71]
	v_mfma_f32_16x16x32_bf16 v[64:67], v[172:175], v[214:217], v[64:67]
	s_barrier
; #define PG8_STAGE(bufoff, gbase, voff) do { _Pragma("unroll") for (int _i = 0; _i < 2; ++_i) \
;         __builtin_amdgcn_global_load_lds((const unsigned*)((const char*)(gbase) + (voff)[_i]), (PG8_LAS unsigned*)(lds + (bufoff) + ldsw + _i * 8192), 16, 0, 0); } while (0)
; #define PG8_LDA(dst, b, h) do { _Pragma("unroll") for (int m = 0; m < 4; ++m) _Pragma("unroll") for (int k = 0; k < 2; ++k) dst[m][k] = *(const PG8_LAS bf16x8*)(lds + PG8_SA(b, h) + aoff + m * 2048 + k * 1024); } while (0)
; #define PG8_MMA(ai, bj, At, Bt) do { __builtin_amdgcn_s_setprio(1); _Pragma("unroll") for (int m = 0; m < 4; ++m) _Pragma("unroll") for (int n = 0; n < 2; ++n) _Pragma("unroll") for (int k = 0; k < 2; ++k) \
;         acc[ai][bj][m][n] = __builtin_amdgcn_mfma_f32_16x16x32_bf16(Bt[n][k], At[m][k], acc[ai][bj][m][n], 0, 0, 0); __builtin_amdgcn_s_setprio(0); } while (0)
; #define PG8_WAIT_V(n) asm volatile("s_waitcnt vmcnt(" #n ")" ::: "memory")
; #define PG8_WAIT_L(n) asm volatile("s_waitcnt lgkmcnt(" #n ")" ::: "memory")
; #define PG8_BAR __builtin_amdgcn_s_barrier()
; #define PG8_SCHED __builtin_amdgcn_sched_barrier(0)
; template <class Epi, class Sched, bool ALIGN_EPI = false, bool SP2 = false>
; __device__ __forceinline__ void gemm_phase(PG8_LAS unsigned char* lds, const Gemm g, const Sched& S, const Epi& E, int tid_in) {
;     ...
;             PG8_LDA(At, 1, 1); PG8_STAGE(PG8_SB(1, 0), b3, voffB); PG8_STAGE(PG8_SB(1, 1), b3 + hstep, voffB); PG8_STAGE(PG8_SA(1, 0), a3, voffA);
;             PG8_WAIT_V(8); PG8_WAIT_L(0); PG8_BAR; PG8_MMA(1, 0, At, B0); PG8_MMA(1, 1, At, B1); PG8_BAR; PG8_SCHED;
	s_add_i32 s36, s61, s0
	s_mov_b32 m0, s36
	ds_read_b128 v[176:179], v193 offset:49152
	global_load_lds_dwordx4 v154, s[98:99]
	s_add_i32 m0, s36, 0x2000
	s_add_u32 s34, s34, 0x40080
	s_addc_u32 s35, s35, 0
	s_add_i32 s36, s62, s0
	global_load_lds_dwordx4 v158, s[98:99]
	s_mov_b32 m0, s36
	ds_read_b128 v[180:183], v193 offset:50176
	global_load_lds_dwordx4 v154, s[34:35]
	s_add_i32 m0, s36, 0x2000
	ds_read_b128 v[194:197], v193 offset:51200
	global_load_lds_dwordx4 v158, s[34:35]
	s_mov_b32 m0, s50
	ds_read_b128 v[198:201], v193 offset:52224
	global_load_lds_dwordx4 v152, s[100:101]
	s_mov_b32 m0, s51
	ds_read_b128 v[202:205], v193 offset:53248
	global_load_lds_dwordx4 v156, s[100:101]
	ds_read_b128 v[206:209], v193 offset:54272
	ds_read_b128 v[210:213], v193 offset:55296
	ds_read_b128 v[214:217], v193 offset:56320
	s_waitcnt vmcnt(8)
	s_waitcnt lgkmcnt(0)
	s_barrier
	v_mfma_f32_16x16x32_bf16 v[60:63], v[128:131], v[176:179], v[60:63]
	v_mfma_f32_16x16x32_bf16 v[56:59], v[136:139], v[176:179], v[56:59]
	v_mfma_f32_16x16x32_bf16 v[44:47], v[128:131], v[194:197], v[44:47]
	v_mfma_f32_16x16x32_bf16 v[40:43], v[136:139], v[194:197], v[40:43]
	v_mfma_f32_16x16x32_bf16 v[28:31], v[128:131], v[202:205], v[28:31]
	v_mfma_f32_16x16x32_bf16 v[24:27], v[136:139], v[202:205], v[24:27]
	v_mfma_f32_16x16x32_bf16 v[12:15], v[128:131], v[210:213], v[12:15]
	v_mfma_f32_16x16x32_bf16 v[8:11], v[136:139], v[210:213], v[8:11]
	v_mfma_f32_16x16x32_bf16 v[60:63], v[132:135], v[180:183], v[60:63]
	v_mfma_f32_16x16x32_bf16 v[56:59], v[140:143], v[180:183], v[56:59]
	v_mfma_f32_16x16x32_bf16 v[44:47], v[132:135], v[198:201], v[44:47]
	v_mfma_f32_16x16x32_bf16 v[40:43], v[140:143], v[198:201], v[40:43]
	v_mfma_f32_16x16x32_bf16 v[28:31], v[132:135], v[206:209], v[28:31]
	v_mfma_f32_16x16x32_bf16 v[24:27], v[140:143], v[206:209], v[24:27]
	v_mfma_f32_16x16x32_bf16 v[12:15], v[132:135], v[214:217], v[12:15]
	v_mfma_f32_16x16x32_bf16 v[8:11], v[140:143], v[214:217], v[8:11]
	v_mfma_f32_16x16x32_bf16 v[52:55], v[144:147], v[176:179], v[52:55]
	v_mfma_f32_16x16x32_bf16 v[48:51], v[168:171], v[176:179], v[48:51]
	v_mfma_f32_16x16x32_bf16 v[36:39], v[144:147], v[194:197], v[36:39]
	v_mfma_f32_16x16x32_bf16 v[32:35], v[168:171], v[194:197], v[32:35]
	v_mfma_f32_16x16x32_bf16 v[20:23], v[144:147], v[202:205], v[20:23]
	v_mfma_f32_16x16x32_bf16 v[16:19], v[168:171], v[202:205], v[16:19]
	v_mfma_f32_16x16x32_bf16 v[4:7], v[144:147], v[210:213], v[4:7]
	v_mfma_f32_16x16x32_bf16 v[0:3], v[168:171], v[210:213], v[0:3]
	v_mfma_f32_16x16x32_bf16 v[52:55], v[148:151], v[180:183], v[52:55]
	v_mfma_f32_16x16x32_bf16 v[48:51], v[172:175], v[180:183], v[48:51]
	v_mfma_f32_16x16x32_bf16 v[36:39], v[148:151], v[198:201], v[36:39]
	v_mfma_f32_16x16x32_bf16 v[32:35], v[172:175], v[198:201], v[32:35]
	v_mfma_f32_16x16x32_bf16 v[20:23], v[148:151], v[206:209], v[20:23]
	v_mfma_f32_16x16x32_bf16 v[16:19], v[172:175], v[206:209], v[16:19]
	v_mfma_f32_16x16x32_bf16 v[4:7], v[148:151], v[214:217], v[4:7]
	v_mfma_f32_16x16x32_bf16 v[0:3], v[172:175], v[214:217], v[0:3]
	s_barrier
	s_add_i32 s60, s60, 2
	s_add_u32 s30, s30, 0x100
	s_addc_u32 s31, s31, 0
	s_add_u32 s58, s58, 0x100
	s_addc_u32 s59, s59, 0
	v_readlane_b32 s98, v248, 0
	s_nop 3
	s_cmp_ge_u32 s98, 0x100
	s_cbranch_scc1 .Lgprio_skip_3
	s_setprio 1

; #define PG8_STAGE(bufoff, gbase, voff) do { _Pragma("unroll") for (int _i = 0; _i < 2; ++_i) \
;         __builtin_amdgcn_global_load_lds((const unsigned*)((const char*)(gbase) + (voff)[_i]), (PG8_LAS unsigned*)(lds + (bufoff) + ldsw + _i * 8192), 16, 0, 0); } while (0)
; #define PG8_LDA(dst, b, h) do { _Pragma("unroll") for (int m = 0; m < 4; ++m) _Pragma("unroll") for (int k = 0; k < 2; ++k) dst[m][k] = *(const PG8_LAS bf16x8*)(lds + PG8_SA(b, h) + aoff + m * 2048 + k * 1024); } while (0)
; #define PG8_LDB(dst, b, h) do { _Pragma("unroll") for (int n = 0; n < 2; ++n) _Pragma("unroll") for (int k = 0; k < 2; ++k) dst[n][k] = *(const PG8_LAS bf16x8*)(lds + PG8_SB(b, h) + boff + n * 2048 + k * 1024); } while (0)
; #define PG8_WAIT_V(n) asm volatile("s_waitcnt vmcnt(" #n ")" ::: "memory")
; #define PG8_WAIT_L(n) asm volatile("s_waitcnt lgkmcnt(" #n ")" ::: "memory")
; #define PG8_BAR __builtin_amdgcn_s_barrier()
; template <class Epi, class Sched, bool ALIGN_EPI = false, bool SP2 = false>
; __device__ __forceinline__ void gemm_phase(PG8_LAS unsigned char* lds, const Gemm g, const Sched& S, const Epi& E, int tid_in) {
;     ...
;         const char* nA = has_next ? (const char*)g.A + (size_t)nxt.pm * tstep : cA; const char* nB = has_next ? (const char*)g.Bt + (size_t)nxt.pn * tstep : cB;
;         for (int t = 0; t < nt; t += 2) {
;             if constexpr (Epi::MIDK) { if (t == Epi::MIDK_T) { if (wr == 0) PG8_BAR; E.mid(acc, cur, wr, wc, fr, fq); if (wr == 1) PG8_BAR; } }
;             const bool last = (t == nt - 2);
;             const char* a1 = cA + (size_t)(t + 1) * kstep;
;             const char* a2 = last ? nA : cA + (size_t)(t + 2) * kstep; const char* b2 = last ? nB : cB + (size_t)(t + 2) * kstep;
;             const char* a3 = a2 + kstep; const char* b3 = b2 + kstep;
;             if (last && has_next) S.a_ready(nxt);
;             if constexpr (SP2) {
;             PG8_LDB(B0, 0, 0); PG8_LDB(B1, 0, 1); PG8_SCHED; PG8_LDA(At, 0, 0); PG8_STAGE(PG8_SA(1, 1), a1 + hstep, voffA);
;             PG8_WAIT_V(8); PG8_WAIT_L(0); PG8_BAR; PG8_MMA(0, 0, At, B0); PG8_MMA(0, 1, At, B1); PG8_BAR; PG8_SCHED;
;             PG8_LDA(At, 0, 1); PG8_STAGE(PG8_SB(0, 0), b2, voffB); PG8_STAGE(PG8_SB(0, 1), b2 + hstep, voffB); PG8_STAGE(PG8_SA(0, 0), a2, voffA);
;             PG8_WAIT_V(8); PG8_WAIT_L(0); PG8_BAR; PG8_MMA(1, 0, At, B0); PG8_MMA(1, 1, At, B1); PG8_BAR; PG8_SCHED;
.LBB0_1237:
	s_ashr_i32 s17, s16, 31
	s_lshl_b64 s[18:19], s[16:17], 19
	s_add_u32 s18, s1, s18
	s_addc_u32 s19, s30, s19
	s_and_b64 s[20:21], s[2:3], exec
	s_cselect_b32 s17, s19, s25
	s_cselect_b32 s54, s18, s24
	s_ashr_i32 s15, s14, 31
	s_lshl_b64 s[20:21], s[14:15], 19
	s_add_u32 s20, s31, s20
	s_addc_u32 s21, s34, s21
	s_and_b64 s[28:29], s[2:3], exec
	s_cselect_b32 s15, s21, s27
	s_cselect_b32 s55, s20, s26
	s_add_u32 s24, s24, 0x40080
	s_addc_u32 s25, s25, 0
	s_add_u32 s56, s26, 0x100
	s_addc_u32 s57, s27, 0
	s_mov_b32 s58, -2
	s_add_u32 s26, s24, 0xfffc0080
	s_addc_u32 s27, s25, -1
	s_cmp_eq_u32 s58, 12
	s_cselect_b32 s29, s17, s27
	s_cselect_b32 s28, s54, s26
	s_cselect_b32 s27, s15, s57
	s_cselect_b32 s26, s55, s56
	s_add_i32 m0, s23, 0xc000
	ds_read_b128 v[144:147], v154
	global_load_lds_dwordx4 v136, s[24:25]
	s_add_i32 m0, s23, 0xe000
	ds_read_b128 v[158:161], v154 offset:1024
	global_load_lds_dwordx4 v138, s[24:25]
	ds_read_b128 v[162:165], v154 offset:2048
	ds_read_b128 v[166:169], v154 offset:3072
	ds_read_b128 v[170:173], v155
	ds_read_b128 v[174:177], v155 offset:1024
	ds_read_b128 v[178:181], v155 offset:2048
	ds_read_b128 v[182:185], v155 offset:3072
	ds_read_b128 v[186:189], v156
	ds_read_b128 v[190:193], v156 offset:1024
	ds_read_b128 v[194:197], v156 offset:2048
	ds_read_b128 v[198:201], v156 offset:3072
	ds_read_b128 v[202:205], v156 offset:4096
	ds_read_b128 v[206:209], v156 offset:5120
	ds_read_b128 v[210:213], v156 offset:6144
	ds_read_b128 v[214:217], v156 offset:7168
	s_waitcnt vmcnt(8)
	s_waitcnt lgkmcnt(0)
	s_barrier
	v_mfma_f32_16x16x32_bf16 v[124:127], v[144:147], v[186:189], 0
	v_mfma_f32_16x16x32_bf16 v[120:123], v[162:165], v[186:189], 0
	v_mfma_f32_16x16x32_bf16 v[108:111], v[144:147], v[194:197], 0
	v_mfma_f32_16x16x32_bf16 v[104:107], v[162:165], v[194:197], 0
	v_mfma_f32_16x16x32_bf16 v[92:95], v[144:147], v[202:205], 0
	v_mfma_f32_16x16x32_bf16 v[88:91], v[162:165], v[202:205], 0
	v_mfma_f32_16x16x32_bf16 v[76:79], v[144:147], v[210:213], 0
	v_mfma_f32_16x16x32_bf16 v[72:75], v[162:165], v[210:213], 0
	v_mfma_f32_16x16x32_bf16 v[124:127], v[158:161], v[190:193], v[124:127]
	v_mfma_f32_16x16x32_bf16 v[120:123], v[166:169], v[190:193], v[120:123]
	v_mfma_f32_16x16x32_bf16 v[108:111], v[158:161], v[198:201], v[108:111]
	v_mfma_f32_16x16x32_bf16 v[104:107], v[166:169], v[198:201], v[104:107]
	v_mfma_f32_16x16x32_bf16 v[92:95], v[158:161], v[206:209], v[92:95]
	v_mfma_f32_16x16x32_bf16 v[88:91], v[166:169], v[206:209], v[88:91]
	v_mfma_f32_16x16x32_bf16 v[76:79], v[158:161], v[214:217], v[76:79]
	v_mfma_f32_16x16x32_bf16 v[72:75], v[166:169], v[214:217], v[72:75]
	v_mfma_f32_16x16x32_bf16 v[116:119], v[170:173], v[186:189], 0
	v_mfma_f32_16x16x32_bf16 v[112:115], v[178:181], v[186:189], 0
	v_mfma_f32_16x16x32_bf16 v[100:103], v[170:173], v[194:197], 0
	v_mfma_f32_16x16x32_bf16 v[96:99], v[178:181], v[194:197], 0
	v_mfma_f32_16x16x32_bf16 v[84:87], v[170:173], v[202:205], 0
	v_mfma_f32_16x16x32_bf16 v[80:83], v[178:181], v[202:205], 0
	v_mfma_f32_16x16x32_bf16 v[68:71], v[170:173], v[210:213], 0
	v_mfma_f32_16x16x32_bf16 v[64:67], v[178:181], v[210:213], 0
	v_mfma_f32_16x16x32_bf16 v[116:119], v[174:177], v[190:193], v[116:119]
	v_mfma_f32_16x16x32_bf16 v[112:115], v[182:185], v[190:193], v[112:115]
	v_mfma_f32_16x16x32_bf16 v[100:103], v[174:177], v[198:201], v[100:103]
	v_mfma_f32_16x16x32_bf16 v[96:99], v[182:185], v[198:201], v[96:99]
	v_mfma_f32_16x16x32_bf16 v[84:87], v[174:177], v[206:209], v[84:87]
	v_mfma_f32_16x16x32_bf16 v[80:83], v[182:185], v[206:209], v[80:83]
	v_mfma_f32_16x16x32_bf16 v[68:71], v[174:177], v[214:217], v[68:71]
	v_mfma_f32_16x16x32_bf16 v[64:67], v[182:185], v[214:217], v[64:67]
	s_barrier
	s_add_u32 s98, s26, s10
	s_addc_u32 s99, s27, s11
	s_add_u32 s100, s28, s10
	s_addc_u32 s101, s29, s11
	s_add_i32 s59, s47, s0
	s_mov_b32 m0, s59
	ds_read_b128 v[186:189], v156 offset:16384
	global_load_lds_dwordx4 v132, s[26:27]
	s_add_i32 m0, s59, 0x2000
	s_add_u32 s60, s26, 0x40000
	s_addc_u32 s61, s27, 0
	s_add_i32 s59, s48, s0
	global_load_lds_dwordx4 v128, s[26:27]
	s_mov_b32 m0, s59
	ds_read_b128 v[190:193], v156 offset:17408
	global_load_lds_dwordx4 v132, s[60:61]
	s_add_i32 m0, s59, 0x2000
	ds_read_b128 v[194:197], v156 offset:18432
	global_load_lds_dwordx4 v128, s[60:61]
	s_mov_b32 m0, s23
	ds_read_b128 v[198:201], v156 offset:19456
	global_load_lds_dwordx4 v134, s[28:29]
	s_mov_b32 m0, s37
	ds_read_b128 v[202:205], v156 offset:20480
	global_load_lds_dwordx4 v130, s[28:29]
	ds_read_b128 v[206:209], v156 offset:21504
	ds_read_b128 v[210:213], v156 offset:22528
	ds_read_b128 v[214:217], v156 offset:23552
	s_waitcnt vmcnt(8)
	s_waitcnt lgkmcnt(0)
	s_barrier
; #define PG8_STAGE(bufoff, gbase, voff) do { _Pragma("unroll") for (int _i = 0; _i < 2; ++_i) \
;         __builtin_amdgcn_global_load_lds((const unsigned*)((const char*)(gbase) + (voff)[_i]), (PG8_LAS unsigned*)(lds + (bufoff) + ldsw + _i * 8192), 16, 0, 0); } while (0)
; #define PG8_LDA(dst, b, h) do { _Pragma("unroll") for (int m = 0; m < 4; ++m) _Pragma("unroll") for (int k = 0; k < 2; ++k) dst[m][k] = *(const PG8_LAS bf16x8*)(lds + PG8_SA(b, h) + aoff + m * 2048 + k * 1024); } while (0)
; #define PG8_LDB(dst, b, h) do { _Pragma("unroll") for (int n = 0; n < 2; ++n) _Pragma("unroll") for (int k = 0; k < 2; ++k) dst[n][k] = *(const PG8_LAS bf16x8*)(lds + PG8_SB(b, h) + boff + n * 2048 + k * 1024); } while (0)
; #define PG8_MMA(ai, bj, At, Bt) do { __builtin_amdgcn_s_setprio(1); _Pragma("unroll") for (int m = 0; m < 4; ++m) _Pragma("unroll") for (int n = 0; n < 2; ++n) _Pragma("unroll") for (int k = 0; k < 2; ++k) \
;         acc[ai][bj][m][n] = __builtin_amdgcn_mfma_f32_16x16x32_bf16(Bt[n][k], At[m][k], acc[ai][bj][m][n], 0, 0, 0); __builtin_amdgcn_s_setprio(0); } while (0)
; #define PG8_WAIT_V(n) asm volatile("s_waitcnt vmcnt(" #n ")" ::: "memory")
; #define PG8_WAIT_L(n) asm volatile("s_waitcnt lgkmcnt(" #n ")" ::: "memory")
; #define PG8_BAR __builtin_amdgcn_s_barrier()
; #define PG8_SCHED __builtin_amdgcn_sched_barrier(0)
; template <class Epi, class Sched, bool ALIGN_EPI = false, bool SP2 = false>
; __device__ __forceinline__ void gemm_phase(PG8_LAS unsigned char* lds, const Gemm g, const Sched& S, const Epi& E, int tid_in) {
;     ...
;             PG8_WAIT_V(8); PG8_WAIT_L(0); PG8_BAR; PG8_MMA(1, 0, At, B0); PG8_MMA(1, 1, At, B1); PG8_BAR; PG8_SCHED;
;             PG8_LDB(B0, 1, 0); PG8_LDB(B1, 1, 1); PG8_SCHED; PG8_LDA(At, 1, 0); PG8_STAGE(PG8_SA(0, 1), a2 + hstep, voffA);
;             PG8_WAIT_V(8); PG8_WAIT_L(0); PG8_BAR; PG8_MMA(0, 0, At, B0); PG8_MMA(0, 1, At, B1); PG8_BAR; PG8_SCHED;
	v_mfma_f32_16x16x32_bf16 v[60:63], v[144:147], v[186:189], 0
	v_mfma_f32_16x16x32_bf16 v[56:59], v[162:165], v[186:189], 0
	v_mfma_f32_16x16x32_bf16 v[44:47], v[144:147], v[194:197], 0
	v_mfma_f32_16x16x32_bf16 v[40:43], v[162:165], v[194:197], 0
	v_mfma_f32_16x16x32_bf16 v[28:31], v[144:147], v[202:205], 0
	v_mfma_f32_16x16x32_bf16 v[24:27], v[162:165], v[202:205], 0
	v_mfma_f32_16x16x32_bf16 v[12:15], v[144:147], v[210:213], 0
	v_mfma_f32_16x16x32_bf16 v[8:11], v[162:165], v[210:213], 0
	v_mfma_f32_16x16x32_bf16 v[60:63], v[158:161], v[190:193], v[60:63]
	v_mfma_f32_16x16x32_bf16 v[56:59], v[166:169], v[190:193], v[56:59]
	v_mfma_f32_16x16x32_bf16 v[44:47], v[158:161], v[198:201], v[44:47]
	v_mfma_f32_16x16x32_bf16 v[40:43], v[166:169], v[198:201], v[40:43]
	v_mfma_f32_16x16x32_bf16 v[28:31], v[158:161], v[206:209], v[28:31]
	v_mfma_f32_16x16x32_bf16 v[24:27], v[166:169], v[206:209], v[24:27]
	v_mfma_f32_16x16x32_bf16 v[12:15], v[158:161], v[214:217], v[12:15]
	v_mfma_f32_16x16x32_bf16 v[8:11], v[166:169], v[214:217], v[8:11]
	v_mfma_f32_16x16x32_bf16 v[52:55], v[170:173], v[186:189], 0
	v_mfma_f32_16x16x32_bf16 v[48:51], v[178:181], v[186:189], 0
	v_mfma_f32_16x16x32_bf16 v[36:39], v[170:173], v[194:197], 0
	v_mfma_f32_16x16x32_bf16 v[32:35], v[178:181], v[194:197], 0
	v_mfma_f32_16x16x32_bf16 v[20:23], v[170:173], v[202:205], 0
	v_mfma_f32_16x16x32_bf16 v[16:19], v[178:181], v[202:205], 0
	v_mfma_f32_16x16x32_bf16 v[4:7], v[170:173], v[210:213], 0
	v_mfma_f32_16x16x32_bf16 v[0:3], v[178:181], v[210:213], 0
	v_mfma_f32_16x16x32_bf16 v[52:55], v[174:177], v[190:193], v[52:55]
	v_mfma_f32_16x16x32_bf16 v[48:51], v[182:185], v[190:193], v[48:51]
	v_mfma_f32_16x16x32_bf16 v[36:39], v[174:177], v[198:201], v[36:39]
	v_mfma_f32_16x16x32_bf16 v[32:35], v[182:185], v[198:201], v[32:35]
	v_mfma_f32_16x16x32_bf16 v[20:23], v[174:177], v[206:209], v[20:23]
	v_mfma_f32_16x16x32_bf16 v[16:19], v[182:185], v[206:209], v[16:19]
	v_mfma_f32_16x16x32_bf16 v[4:7], v[174:177], v[214:217], v[4:7]
	v_mfma_f32_16x16x32_bf16 v[0:3], v[182:185], v[214:217], v[0:3]
	s_barrier
	s_add_i32 s59, 0, 0x18000
	s_add_i32 s60, 0, 0x1c000
	s_add_u32 s28, s28, 0x40000
	s_addc_u32 s29, s29, 0
	s_mov_b32 m0, s38
	v_add_u32_e32 v157, s59, v151
	global_load_lds_dwordx4 v134, s[28:29]
	s_mov_b32 m0, s39
	ds_read_b128 v[144:147], v157
	global_load_lds_dwordx4 v130, s[28:29]
	ds_read_b128 v[158:161], v157 offset:1024
	ds_read_b128 v[162:165], v157 offset:2048
	ds_read_b128 v[166:169], v157 offset:3072
	v_add_u32_e32 v157, s60, v151
	ds_read_b128 v[170:173], v157
	ds_read_b128 v[174:177], v157 offset:1024
	ds_read_b128 v[178:181], v157 offset:2048
	ds_read_b128 v[182:185], v157 offset:3072
	ds_read_b128 v[186:189], v156 offset:32768
	ds_read_b128 v[190:193], v156 offset:33792
	ds_read_b128 v[194:197], v156 offset:34816
	ds_read_b128 v[198:201], v156 offset:35840
	ds_read_b128 v[202:205], v156 offset:36864
	ds_read_b128 v[206:209], v156 offset:37888
	ds_read_b128 v[210:213], v156 offset:38912
	ds_read_b128 v[214:217], v156 offset:39936
	s_waitcnt vmcnt(8)
	s_waitcnt lgkmcnt(0)
	s_barrier
	v_mfma_f32_16x16x32_bf16 v[124:127], v[144:147], v[186:189], v[124:127]
	v_mfma_f32_16x16x32_bf16 v[120:123], v[162:165], v[186:189], v[120:123]
	v_mfma_f32_16x16x32_bf16 v[108:111], v[144:147], v[194:197], v[108:111]
	v_mfma_f32_16x16x32_bf16 v[104:107], v[162:165], v[194:197], v[104:107]
	v_mfma_f32_16x16x32_bf16 v[92:95], v[144:147], v[202:205], v[92:95]
	v_mfma_f32_16x16x32_bf16 v[88:91], v[162:165], v[202:205], v[88:91]
	v_mfma_f32_16x16x32_bf16 v[76:79], v[144:147], v[210:213], v[76:79]
	v_mfma_f32_16x16x32_bf16 v[72:75], v[162:165], v[210:213], v[72:75]
	v_mfma_f32_16x16x32_bf16 v[124:127], v[158:161], v[190:193], v[124:127]
	v_mfma_f32_16x16x32_bf16 v[120:123], v[166:169], v[190:193], v[120:123]
	v_mfma_f32_16x16x32_bf16 v[108:111], v[158:161], v[198:201], v[108:111]
	v_mfma_f32_16x16x32_bf16 v[104:107], v[166:169], v[198:201], v[104:107]
	v_mfma_f32_16x16x32_bf16 v[92:95], v[158:161], v[206:209], v[92:95]
	v_mfma_f32_16x16x32_bf16 v[88:91], v[166:169], v[206:209], v[88:91]
	v_mfma_f32_16x16x32_bf16 v[76:79], v[158:161], v[214:217], v[76:79]
	v_mfma_f32_16x16x32_bf16 v[72:75], v[166:169], v[214:217], v[72:75]
	v_mfma_f32_16x16x32_bf16 v[116:119], v[170:173], v[186:189], v[116:119]
	v_mfma_f32_16x16x32_bf16 v[112:115], v[178:181], v[186:189], v[112:115]
	v_mfma_f32_16x16x32_bf16 v[100:103], v[170:173], v[194:197], v[100:103]
	v_mfma_f32_16x16x32_bf16 v[96:99], v[178:181], v[194:197], v[96:99]
	v_mfma_f32_16x16x32_bf16 v[84:87], v[170:173], v[202:205], v[84:87]
	v_mfma_f32_16x16x32_bf16 v[80:83], v[178:181], v[202:205], v[80:83]
	v_mfma_f32_16x16x32_bf16 v[68:71], v[170:173], v[210:213], v[68:71]
	v_mfma_f32_16x16x32_bf16 v[64:67], v[178:181], v[210:213], v[64:67]
	v_mfma_f32_16x16x32_bf16 v[116:119], v[174:177], v[190:193], v[116:119]
	v_mfma_f32_16x16x32_bf16 v[112:115], v[182:185], v[190:193], v[112:115]
	v_mfma_f32_16x16x32_bf16 v[100:103], v[174:177], v[198:201], v[100:103]
	v_mfma_f32_16x16x32_bf16 v[96:99], v[182:185], v[198:201], v[96:99]
	v_mfma_f32_16x16x32_bf16 v[84:87], v[174:177], v[206:209], v[84:87]
	v_mfma_f32_16x16x32_bf16 v[80:83], v[182:185], v[206:209], v[80:83]
	v_mfma_f32_16x16x32_bf16 v[68:71], v[174:177], v[214:217], v[68:71]
	v_mfma_f32_16x16x32_bf16 v[64:67], v[182:185], v[214:217], v[64:67]
	s_barrier
; #define PG8_STAGE(bufoff, gbase, voff) do { _Pragma("unroll") for (int _i = 0; _i < 2; ++_i) \
;         __builtin_amdgcn_global_load_lds((const unsigned*)((const char*)(gbase) + (voff)[_i]), (PG8_LAS unsigned*)(lds + (bufoff) + ldsw + _i * 8192), 16, 0, 0); } while (0)
; #define PG8_LDA(dst, b, h) do { _Pragma("unroll") for (int m = 0; m < 4; ++m) _Pragma("unroll") for (int k = 0; k < 2; ++k) dst[m][k] = *(const PG8_LAS bf16x8*)(lds + PG8_SA(b, h) + aoff + m * 2048 + k * 1024); } while (0)
; #define PG8_MMA(ai, bj, At, Bt) do { __builtin_amdgcn_s_setprio(1); _Pragma("unroll") for (int m = 0; m < 4; ++m) _Pragma("unroll") for (int n = 0; n < 2; ++n) _Pragma("unroll") for (int k = 0; k < 2; ++k) \
;         acc[ai][bj][m][n] = __builtin_amdgcn_mfma_f32_16x16x32_bf16(Bt[n][k], At[m][k], acc[ai][bj][m][n], 0, 0, 0); __builtin_amdgcn_s_setprio(0); } while (0)
; #define PG8_WAIT_V(n) asm volatile("s_waitcnt vmcnt(" #n ")" ::: "memory")
; #define PG8_WAIT_L(n) asm volatile("s_waitcnt lgkmcnt(" #n ")" ::: "memory")
; #define PG8_BAR __builtin_amdgcn_s_barrier()
; #define PG8_SCHED __builtin_amdgcn_sched_barrier(0)
; template <class Epi, class Sched, bool ALIGN_EPI = false, bool SP2 = false>
; __device__ __forceinline__ void gemm_phase(PG8_LAS unsigned char* lds, const Gemm g, const Sched& S, const Epi& E, int tid_in) {
;     ...
;             PG8_LDA(At, 1, 1); PG8_STAGE(PG8_SB(1, 0), b3, voffB); PG8_STAGE(PG8_SB(1, 1), b3 + hstep, voffB); PG8_STAGE(PG8_SA(1, 0), a3, voffA);
;             PG8_WAIT_V(8); PG8_WAIT_L(0); PG8_BAR; PG8_MMA(1, 0, At, B0); PG8_MMA(1, 1, At, B1); PG8_BAR; PG8_SCHED;
	s_add_i32 s28, s59, s0
	s_mov_b32 m0, s28
	ds_read_b128 v[186:189], v156 offset:49152
	global_load_lds_dwordx4 v132, s[98:99]
	s_add_i32 m0, s28, 0x2000
	s_add_u32 s26, s26, 0x40080
	s_addc_u32 s27, s27, 0
	s_add_i32 s28, s60, s0
	global_load_lds_dwordx4 v128, s[98:99]
	s_mov_b32 m0, s28
	ds_read_b128 v[190:193], v156 offset:50176
	global_load_lds_dwordx4 v132, s[26:27]
	s_add_i32 m0, s28, 0x2000
	ds_read_b128 v[194:197], v156 offset:51200
	global_load_lds_dwordx4 v128, s[26:27]
	s_mov_b32 m0, s44
	ds_read_b128 v[198:201], v156 offset:52224
	global_load_lds_dwordx4 v134, s[100:101]
	s_mov_b32 m0, s45
	ds_read_b128 v[202:205], v156 offset:53248
	global_load_lds_dwordx4 v130, s[100:101]
	ds_read_b128 v[206:209], v156 offset:54272
	ds_read_b128 v[210:213], v156 offset:55296
	ds_read_b128 v[214:217], v156 offset:56320
	s_waitcnt vmcnt(8)
	s_waitcnt lgkmcnt(0)
	s_barrier
	v_mfma_f32_16x16x32_bf16 v[60:63], v[144:147], v[186:189], v[60:63]
	v_mfma_f32_16x16x32_bf16 v[56:59], v[162:165], v[186:189], v[56:59]
	v_mfma_f32_16x16x32_bf16 v[44:47], v[144:147], v[194:197], v[44:47]
	v_mfma_f32_16x16x32_bf16 v[40:43], v[162:165], v[194:197], v[40:43]
	v_mfma_f32_16x16x32_bf16 v[28:31], v[144:147], v[202:205], v[28:31]
	v_mfma_f32_16x16x32_bf16 v[24:27], v[162:165], v[202:205], v[24:27]
	v_mfma_f32_16x16x32_bf16 v[12:15], v[144:147], v[210:213], v[12:15]
	v_mfma_f32_16x16x32_bf16 v[8:11], v[162:165], v[210:213], v[8:11]
	v_mfma_f32_16x16x32_bf16 v[60:63], v[158:161], v[190:193], v[60:63]
	v_mfma_f32_16x16x32_bf16 v[56:59], v[166:169], v[190:193], v[56:59]
	v_mfma_f32_16x16x32_bf16 v[44:47], v[158:161], v[198:201], v[44:47]
	v_mfma_f32_16x16x32_bf16 v[40:43], v[166:169], v[198:201], v[40:43]
	v_mfma_f32_16x16x32_bf16 v[28:31], v[158:161], v[206:209], v[28:31]
	v_mfma_f32_16x16x32_bf16 v[24:27], v[166:169], v[206:209], v[24:27]
	v_mfma_f32_16x16x32_bf16 v[12:15], v[158:161], v[214:217], v[12:15]
	v_mfma_f32_16x16x32_bf16 v[8:11], v[166:169], v[214:217], v[8:11]
	v_mfma_f32_16x16x32_bf16 v[52:55], v[170:173], v[186:189], v[52:55]
	v_mfma_f32_16x16x32_bf16 v[48:51], v[178:181], v[186:189], v[48:51]
	v_mfma_f32_16x16x32_bf16 v[36:39], v[170:173], v[194:197], v[36:39]
	v_mfma_f32_16x16x32_bf16 v[32:35], v[178:181], v[194:197], v[32:35]
	v_mfma_f32_16x16x32_bf16 v[20:23], v[170:173], v[202:205], v[20:23]
	v_mfma_f32_16x16x32_bf16 v[16:19], v[178:181], v[202:205], v[16:19]
	v_mfma_f32_16x16x32_bf16 v[4:7], v[170:173], v[210:213], v[4:7]
	v_mfma_f32_16x16x32_bf16 v[0:3], v[178:181], v[210:213], v[0:3]
	v_mfma_f32_16x16x32_bf16 v[52:55], v[174:177], v[190:193], v[52:55]
	v_mfma_f32_16x16x32_bf16 v[48:51], v[182:185], v[190:193], v[48:51]
	v_mfma_f32_16x16x32_bf16 v[36:39], v[174:177], v[198:201], v[36:39]
	v_mfma_f32_16x16x32_bf16 v[32:35], v[182:185], v[198:201], v[32:35]
	v_mfma_f32_16x16x32_bf16 v[20:23], v[174:177], v[206:209], v[20:23]
	v_mfma_f32_16x16x32_bf16 v[16:19], v[182:185], v[206:209], v[16:19]
	v_mfma_f32_16x16x32_bf16 v[4:7], v[174:177], v[214:217], v[4:7]
	v_mfma_f32_16x16x32_bf16 v[0:3], v[182:185], v[214:217], v[0:3]
	s_barrier
	s_add_i32 s58, s58, 2
	s_add_u32 s24, s24, 0x100
	s_addc_u32 s25, s25, 0
	s_add_u32 s56, s56, 0x100
	s_addc_u32 s57, s57, 0
	v_readlane_b32 s98, v248, 0
	s_nop 3
	s_cmp_ge_u32 s98, 0x100
	s_cbranch_scc1 .Lgprio_skip_4
	s_setprio 1

; #define PG8_STAGE(bufoff, gbase, voff) do { _Pragma("unroll") for (int _i = 0; _i < 2; ++_i) \
;         __builtin_amdgcn_global_load_lds((const unsigned*)((const char*)(gbase) + (voff)[_i]), (PG8_LAS unsigned*)(lds + (bufoff) + ldsw + _i * 8192), 16, 0, 0); } while (0)
; #define PG8_LDA(dst, b, h) do { _Pragma("unroll") for (int m = 0; m < 4; ++m) _Pragma("unroll") for (int k = 0; k < 2; ++k) dst[m][k] = *(const PG8_LAS bf16x8*)(lds + PG8_SA(b, h) + aoff + m * 2048 + k * 1024); } while (0)
; #define PG8_LDB(dst, b, h) do { _Pragma("unroll") for (int n = 0; n < 2; ++n) _Pragma("unroll") for (int k = 0; k < 2; ++k) dst[n][k] = *(const PG8_LAS bf16x8*)(lds + PG8_SB(b, h) + boff + n * 2048 + k * 1024); } while (0)
; #define PG8_MMA(ai, bj, At, Bt) do { __builtin_amdgcn_s_setprio(1); _Pragma("unroll") for (int m = 0; m < 4; ++m) _Pragma("unroll") for (int n = 0; n < 2; ++n) _Pragma("unroll") for (int k = 0; k < 2; ++k) \
;         acc[ai][bj][m][n] = __builtin_amdgcn_mfma_f32_16x16x32_bf16(Bt[n][k], At[m][k], acc[ai][bj][m][n], 0, 0, 0); __builtin_amdgcn_s_setprio(0); } while (0)
; #define PG8_WAIT_V(n) asm volatile("s_waitcnt vmcnt(" #n ")" ::: "memory")
; #define PG8_WAIT_L(n) asm volatile("s_waitcnt lgkmcnt(" #n ")" ::: "memory")
; template <class Epi, class Sched, bool ALIGN_EPI = false, bool SP2 = false>
; __device__ __forceinline__ void gemm_phase(PG8_LAS unsigned char* lds, const Gemm g, const Sched& S, const Epi& E, int tid_in) {
;     ...
;             const bool last = (t == nt - 2);
;             const char* a1 = cA + (size_t)(t + 1) * kstep;
;             const char* a2 = last ? nA : cA + (size_t)(t + 2) * kstep; const char* b2 = last ? nB : cB + (size_t)(t + 2) * kstep;
;             const char* a3 = a2 + kstep; const char* b3 = b2 + kstep;
;             if (last && has_next) S.a_ready(nxt);
;             if constexpr (SP2) {
;             PG8_LDB(B0, 0, 0); PG8_LDB(B1, 0, 1); PG8_SCHED; PG8_LDA(At, 0, 0); PG8_STAGE(PG8_SA(1, 1), a1 + hstep, voffA);
;             PG8_WAIT_V(8); PG8_WAIT_L(0); PG8_BAR; PG8_MMA(0, 0, At, B0); PG8_MMA(0, 1, At, B1); PG8_BAR; PG8_SCHED;
;             PG8_LDA(At, 0, 1); PG8_STAGE(PG8_SB(0, 0), b2, voffB); PG8_STAGE(PG8_SB(0, 1), b2 + hstep, voffB); PG8_STAGE(PG8_SA(0, 0), a2, voffA);
;             PG8_WAIT_V(8); PG8_WAIT_L(0); PG8_BAR; PG8_MMA(1, 0, At, B0); PG8_MMA(1, 1, At, B1); PG8_BAR; PG8_SCHED;
.LBB0_1320:
	s_add_u32 s48, s22, 0x100
	s_addc_u32 s49, s23, 0
	s_mov_b32 s50, -2
	s_waitcnt vmcnt(0)
	s_add_u32 s2, s20, 0x100
	s_addc_u32 s3, s21, 0
	s_cmp_eq_u32 s50, 40
	s_cselect_b32 s25, s17, s3
	s_cselect_b32 s24, s16, s2
	s_cselect_b32 s23, s19, s49
	s_cselect_b32 s22, s18, s48
	s_add_i32 m0, s34, 0xc000
	ds_read_b128 v[128:131], v195
	global_load_lds_dwordx4 v168, s[20:21]
	s_add_i32 m0, s34, 0xe000
	ds_read_b128 v[132:135], v195 offset:1024
	global_load_lds_dwordx4 v170, s[20:21]
	ds_read_b128 v[136:139], v195 offset:2048
	ds_read_b128 v[140:143], v195 offset:3072
	ds_read_b128 v[144:147], v196
	ds_read_b128 v[148:151], v196 offset:1024
	ds_read_b128 v[152:155], v196 offset:2048
	ds_read_b128 v[156:159], v196 offset:3072
	ds_read_b128 v[176:179], v197
	ds_read_b128 v[180:183], v197 offset:1024
	ds_read_b128 v[184:187], v197 offset:2048
	ds_read_b128 v[188:191], v197 offset:3072
	ds_read_b128 v[198:201], v197 offset:4096
	ds_read_b128 v[202:205], v197 offset:5120
	ds_read_b128 v[206:209], v197 offset:6144
	ds_read_b128 v[210:213], v197 offset:7168
	s_waitcnt vmcnt(8)
	s_waitcnt lgkmcnt(0)
	s_barrier
	v_mfma_f32_16x16x32_bf16 v[120:123], v[128:131], v[176:179], 0
	v_mfma_f32_16x16x32_bf16 v[124:127], v[136:139], v[176:179], 0
	v_mfma_f32_16x16x32_bf16 v[104:107], v[128:131], v[184:187], 0
	v_mfma_f32_16x16x32_bf16 v[108:111], v[136:139], v[184:187], 0
	v_mfma_f32_16x16x32_bf16 v[88:91], v[128:131], v[198:201], 0
	v_mfma_f32_16x16x32_bf16 v[92:95], v[136:139], v[198:201], 0
	v_mfma_f32_16x16x32_bf16 v[72:75], v[128:131], v[206:209], 0
	v_mfma_f32_16x16x32_bf16 v[76:79], v[136:139], v[206:209], 0
	v_mfma_f32_16x16x32_bf16 v[120:123], v[132:135], v[180:183], v[120:123]
	v_mfma_f32_16x16x32_bf16 v[124:127], v[140:143], v[180:183], v[124:127]
	v_mfma_f32_16x16x32_bf16 v[104:107], v[132:135], v[188:191], v[104:107]
	v_mfma_f32_16x16x32_bf16 v[108:111], v[140:143], v[188:191], v[108:111]
	v_mfma_f32_16x16x32_bf16 v[88:91], v[132:135], v[202:205], v[88:91]
	v_mfma_f32_16x16x32_bf16 v[92:95], v[140:143], v[202:205], v[92:95]
	v_mfma_f32_16x16x32_bf16 v[72:75], v[132:135], v[210:213], v[72:75]
	v_mfma_f32_16x16x32_bf16 v[76:79], v[140:143], v[210:213], v[76:79]
	v_mfma_f32_16x16x32_bf16 v[112:115], v[144:147], v[176:179], 0
	v_mfma_f32_16x16x32_bf16 v[116:119], v[152:155], v[176:179], 0
	v_mfma_f32_16x16x32_bf16 v[96:99], v[144:147], v[184:187], 0
	v_mfma_f32_16x16x32_bf16 v[100:103], v[152:155], v[184:187], 0
	v_mfma_f32_16x16x32_bf16 v[80:83], v[144:147], v[198:201], 0
	v_mfma_f32_16x16x32_bf16 v[84:87], v[152:155], v[198:201], 0
	v_mfma_f32_16x16x32_bf16 v[64:67], v[144:147], v[206:209], 0
	v_mfma_f32_16x16x32_bf16 v[68:71], v[152:155], v[206:209], 0
	v_mfma_f32_16x16x32_bf16 v[112:115], v[148:151], v[180:183], v[112:115]
	v_mfma_f32_16x16x32_bf16 v[116:119], v[156:159], v[180:183], v[116:119]
	v_mfma_f32_16x16x32_bf16 v[96:99], v[148:151], v[188:191], v[96:99]
	v_mfma_f32_16x16x32_bf16 v[100:103], v[156:159], v[188:191], v[100:103]
	v_mfma_f32_16x16x32_bf16 v[80:83], v[148:151], v[202:205], v[80:83]
	v_mfma_f32_16x16x32_bf16 v[84:87], v[156:159], v[202:205], v[84:87]
	v_mfma_f32_16x16x32_bf16 v[64:67], v[148:151], v[210:213], v[64:67]
	v_mfma_f32_16x16x32_bf16 v[68:71], v[156:159], v[210:213], v[68:71]
	s_barrier
	s_add_u32 s98, s22, s10
	s_addc_u32 s99, s23, s11
	s_add_u32 s100, s24, s10
	s_addc_u32 s101, s25, s11
	s_add_i32 s20, s42, s31
	s_mov_b32 m0, s20
	ds_read_b128 v[176:179], v197 offset:16384
	global_load_lds_dwordx4 v162, s[22:23]
	s_add_i32 m0, s20, 0x2000
	s_add_u32 s20, s22, 0xb0000
	s_addc_u32 s21, s23, 0
	s_add_i32 s51, s43, s31
	global_load_lds_dwordx4 v166, s[22:23]
	s_mov_b32 m0, s51
	ds_read_b128 v[180:183], v197 offset:17408
	global_load_lds_dwordx4 v162, s[20:21]
	s_add_i32 m0, s51, 0x2000
	ds_read_b128 v[184:187], v197 offset:18432
	global_load_lds_dwordx4 v166, s[20:21]
	s_mov_b32 m0, s34
	ds_read_b128 v[188:191], v197 offset:19456
	global_load_lds_dwordx4 v160, s[24:25]
	s_mov_b32 m0, s35
	ds_read_b128 v[198:201], v197 offset:20480
	global_load_lds_dwordx4 v164, s[24:25]
	ds_read_b128 v[202:205], v197 offset:21504
	ds_read_b128 v[206:209], v197 offset:22528
	ds_read_b128 v[210:213], v197 offset:23552
	s_waitcnt vmcnt(8)
	s_waitcnt lgkmcnt(0)
	s_barrier
	v_mfma_f32_16x16x32_bf16 v[56:59], v[128:131], v[176:179], 0
	v_mfma_f32_16x16x32_bf16 v[60:63], v[136:139], v[176:179], 0
	v_mfma_f32_16x16x32_bf16 v[40:43], v[128:131], v[184:187], 0
	v_mfma_f32_16x16x32_bf16 v[44:47], v[136:139], v[184:187], 0
	v_mfma_f32_16x16x32_bf16 v[24:27], v[128:131], v[198:201], 0
	v_mfma_f32_16x16x32_bf16 v[28:31], v[136:139], v[198:201], 0
	v_mfma_f32_16x16x32_bf16 v[8:11], v[128:131], v[206:209], 0
	v_mfma_f32_16x16x32_bf16 v[12:15], v[136:139], v[206:209], 0
	v_mfma_f32_16x16x32_bf16 v[56:59], v[132:135], v[180:183], v[56:59]
	v_mfma_f32_16x16x32_bf16 v[60:63], v[140:143], v[180:183], v[60:63]
	v_mfma_f32_16x16x32_bf16 v[40:43], v[132:135], v[188:191], v[40:43]
	v_mfma_f32_16x16x32_bf16 v[44:47], v[140:143], v[188:191], v[44:47]
	v_mfma_f32_16x16x32_bf16 v[24:27], v[132:135], v[202:205], v[24:27]
	v_mfma_f32_16x16x32_bf16 v[28:31], v[140:143], v[202:205], v[28:31]
	v_mfma_f32_16x16x32_bf16 v[8:11], v[132:135], v[210:213], v[8:11]
	v_mfma_f32_16x16x32_bf16 v[12:15], v[140:143], v[210:213], v[12:15]
	v_mfma_f32_16x16x32_bf16 v[48:51], v[144:147], v[176:179], 0
	v_mfma_f32_16x16x32_bf16 v[52:55], v[152:155], v[176:179], 0
	v_mfma_f32_16x16x32_bf16 v[32:35], v[144:147], v[184:187], 0
	v_mfma_f32_16x16x32_bf16 v[36:39], v[152:155], v[184:187], 0
	v_mfma_f32_16x16x32_bf16 v[16:19], v[144:147], v[198:201], 0
	v_mfma_f32_16x16x32_bf16 v[20:23], v[152:155], v[198:201], 0
	v_mfma_f32_16x16x32_bf16 v[4:7], v[144:147], v[206:209], 0
	v_mfma_f32_16x16x32_bf16 v[0:3], v[152:155], v[206:209], 0
	v_mfma_f32_16x16x32_bf16 v[48:51], v[148:151], v[180:183], v[48:51]
	v_mfma_f32_16x16x32_bf16 v[52:55], v[156:159], v[180:183], v[52:55]
	v_mfma_f32_16x16x32_bf16 v[32:35], v[148:151], v[188:191], v[32:35]
	v_mfma_f32_16x16x32_bf16 v[36:39], v[156:159], v[188:191], v[36:39]
	v_mfma_f32_16x16x32_bf16 v[16:19], v[148:151], v[202:205], v[16:19]
	v_mfma_f32_16x16x32_bf16 v[20:23], v[156:159], v[202:205], v[20:23]
	v_mfma_f32_16x16x32_bf16 v[4:7], v[148:151], v[210:213], v[4:7]
	v_mfma_f32_16x16x32_bf16 v[0:3], v[156:159], v[210:213], v[0:3]
	s_barrier
; #define PG8_STAGE(bufoff, gbase, voff) do { _Pragma("unroll") for (int _i = 0; _i < 2; ++_i) \
;         __builtin_amdgcn_global_load_lds((const unsigned*)((const char*)(gbase) + (voff)[_i]), (PG8_LAS unsigned*)(lds + (bufoff) + ldsw + _i * 8192), 16, 0, 0); } while (0)
; #define PG8_LDA(dst, b, h) do { _Pragma("unroll") for (int m = 0; m < 4; ++m) _Pragma("unroll") for (int k = 0; k < 2; ++k) dst[m][k] = *(const PG8_LAS bf16x8*)(lds + PG8_SA(b, h) + aoff + m * 2048 + k * 1024); } while (0)
; #define PG8_LDB(dst, b, h) do { _Pragma("unroll") for (int n = 0; n < 2; ++n) _Pragma("unroll") for (int k = 0; k < 2; ++k) dst[n][k] = *(const PG8_LAS bf16x8*)(lds + PG8_SB(b, h) + boff + n * 2048 + k * 1024); } while (0)
; #define PG8_MMA(ai, bj, At, Bt) do { __builtin_amdgcn_s_setprio(1); _Pragma("unroll") for (int m = 0; m < 4; ++m) _Pragma("unroll") for (int n = 0; n < 2; ++n) _Pragma("unroll") for (int k = 0; k < 2; ++k) \
;         acc[ai][bj][m][n] = __builtin_amdgcn_mfma_f32_16x16x32_bf16(Bt[n][k], At[m][k], acc[ai][bj][m][n], 0, 0, 0); __builtin_amdgcn_s_setprio(0); } while (0)
; #define PG8_WAIT_V(n) asm volatile("s_waitcnt vmcnt(" #n ")" ::: "memory")
; #define PG8_WAIT_L(n) asm volatile("s_waitcnt lgkmcnt(" #n ")" ::: "memory")
; #define PG8_BAR __builtin_amdgcn_s_barrier()
; #define PG8_SCHED __builtin_amdgcn_sched_barrier(0)
; template <class Epi, class Sched, bool ALIGN_EPI = false, bool SP2 = false>
; __device__ __forceinline__ void gemm_phase(PG8_LAS unsigned char* lds, const Gemm g, const Sched& S, const Epi& E, int tid_in) {
;     ...
;             PG8_LDB(B0, 1, 0); PG8_LDB(B1, 1, 1); PG8_SCHED; PG8_LDA(At, 1, 0); PG8_STAGE(PG8_SA(0, 1), a2 + hstep, voffA);
;             PG8_WAIT_V(8); PG8_WAIT_L(0); PG8_BAR; PG8_MMA(0, 0, At, B0); PG8_MMA(0, 1, At, B1); PG8_BAR; PG8_SCHED;
;             PG8_LDA(At, 1, 1); PG8_STAGE(PG8_SB(1, 0), b3, voffB); PG8_STAGE(PG8_SB(1, 1), b3 + hstep, voffB); PG8_STAGE(PG8_SA(1, 0), a3, voffA);
;             PG8_WAIT_V(8); PG8_WAIT_L(0); PG8_BAR; PG8_MMA(1, 0, At, B0); PG8_MMA(1, 1, At, B1); PG8_BAR; PG8_SCHED;
	s_add_i32 s51, 0, 0x18000
	s_add_i32 s52, 0, 0x1c000
	s_add_u32 s20, s24, 0xb0000
	s_addc_u32 s21, s25, 0
	s_mov_b32 m0, s36
	s_nop 0
	global_load_lds_dwordx4 v160, s[20:21]
	s_mov_b32 m0, s37
	s_nop 0
	global_load_lds_dwordx4 v164, s[20:21]
	v_add_u32_e32 v140, s51, v193
	v_add_u32_e32 v156, s52, v193
	ds_read_b128 v[128:131], v140
	ds_read_b128 v[132:135], v140 offset:1024
	ds_read_b128 v[136:139], v140 offset:2048
	ds_read_b128 v[140:143], v140 offset:3072
	ds_read_b128 v[144:147], v156
	ds_read_b128 v[148:151], v156 offset:1024
	ds_read_b128 v[152:155], v156 offset:2048
	ds_read_b128 v[156:159], v156 offset:3072
	ds_read_b128 v[176:179], v197 offset:32768
	ds_read_b128 v[180:183], v197 offset:33792
	ds_read_b128 v[184:187], v197 offset:34816
	ds_read_b128 v[188:191], v197 offset:35840
	ds_read_b128 v[198:201], v197 offset:36864
	ds_read_b128 v[202:205], v197 offset:37888
	ds_read_b128 v[206:209], v197 offset:38912
	ds_read_b128 v[210:213], v197 offset:39936
	s_waitcnt vmcnt(8)
	s_waitcnt lgkmcnt(0)
	s_barrier
	v_mfma_f32_16x16x32_bf16 v[120:123], v[128:131], v[176:179], v[120:123]
	v_mfma_f32_16x16x32_bf16 v[124:127], v[136:139], v[176:179], v[124:127]
	v_mfma_f32_16x16x32_bf16 v[104:107], v[128:131], v[184:187], v[104:107]
	v_mfma_f32_16x16x32_bf16 v[108:111], v[136:139], v[184:187], v[108:111]
	v_mfma_f32_16x16x32_bf16 v[88:91], v[128:131], v[198:201], v[88:91]
	v_mfma_f32_16x16x32_bf16 v[92:95], v[136:139], v[198:201], v[92:95]
	v_mfma_f32_16x16x32_bf16 v[72:75], v[128:131], v[206:209], v[72:75]
	v_mfma_f32_16x16x32_bf16 v[76:79], v[136:139], v[206:209], v[76:79]
	v_mfma_f32_16x16x32_bf16 v[120:123], v[132:135], v[180:183], v[120:123]
	v_mfma_f32_16x16x32_bf16 v[124:127], v[140:143], v[180:183], v[124:127]
	v_mfma_f32_16x16x32_bf16 v[104:107], v[132:135], v[188:191], v[104:107]
	v_mfma_f32_16x16x32_bf16 v[108:111], v[140:143], v[188:191], v[108:111]
	v_mfma_f32_16x16x32_bf16 v[88:91], v[132:135], v[202:205], v[88:91]
	v_mfma_f32_16x16x32_bf16 v[92:95], v[140:143], v[202:205], v[92:95]
	v_mfma_f32_16x16x32_bf16 v[72:75], v[132:135], v[210:213], v[72:75]
	v_mfma_f32_16x16x32_bf16 v[76:79], v[140:143], v[210:213], v[76:79]
	v_mfma_f32_16x16x32_bf16 v[112:115], v[144:147], v[176:179], v[112:115]
	v_mfma_f32_16x16x32_bf16 v[116:119], v[152:155], v[176:179], v[116:119]
	v_mfma_f32_16x16x32_bf16 v[96:99], v[144:147], v[184:187], v[96:99]
	v_mfma_f32_16x16x32_bf16 v[100:103], v[152:155], v[184:187], v[100:103]
	v_mfma_f32_16x16x32_bf16 v[80:83], v[144:147], v[198:201], v[80:83]
	v_mfma_f32_16x16x32_bf16 v[84:87], v[152:155], v[198:201], v[84:87]
	v_mfma_f32_16x16x32_bf16 v[64:67], v[144:147], v[206:209], v[64:67]
	v_mfma_f32_16x16x32_bf16 v[68:71], v[152:155], v[206:209], v[68:71]
	v_mfma_f32_16x16x32_bf16 v[112:115], v[148:151], v[180:183], v[112:115]
	v_mfma_f32_16x16x32_bf16 v[116:119], v[156:159], v[180:183], v[116:119]
	v_mfma_f32_16x16x32_bf16 v[96:99], v[148:151], v[188:191], v[96:99]
	v_mfma_f32_16x16x32_bf16 v[100:103], v[156:159], v[188:191], v[100:103]
	v_mfma_f32_16x16x32_bf16 v[80:83], v[148:151], v[202:205], v[80:83]
	v_mfma_f32_16x16x32_bf16 v[84:87], v[156:159], v[202:205], v[84:87]
	v_mfma_f32_16x16x32_bf16 v[64:67], v[148:151], v[210:213], v[64:67]
	v_mfma_f32_16x16x32_bf16 v[68:71], v[156:159], v[210:213], v[68:71]
	s_barrier
	s_add_i32 s20, s51, s31
	s_mov_b32 m0, s20
	ds_read_b128 v[176:179], v197 offset:49152
	global_load_lds_dwordx4 v162, s[98:99]
	s_add_i32 m0, s20, 0x2000
	s_add_u32 s20, s22, 0xb0080
	s_addc_u32 s21, s23, 0
	s_add_i32 s22, s52, s31
	global_load_lds_dwordx4 v166, s[98:99]
	s_mov_b32 m0, s22
	ds_read_b128 v[180:183], v197 offset:50176
	global_load_lds_dwordx4 v162, s[20:21]
	s_add_i32 m0, s22, 0x2000
	ds_read_b128 v[184:187], v197 offset:51200
	global_load_lds_dwordx4 v166, s[20:21]
	s_mov_b32 m0, s39
	ds_read_b128 v[188:191], v197 offset:52224
	global_load_lds_dwordx4 v160, s[100:101]
	s_mov_b32 m0, s40
	ds_read_b128 v[198:201], v197 offset:53248
	global_load_lds_dwordx4 v164, s[100:101]
	ds_read_b128 v[202:205], v197 offset:54272
	ds_read_b128 v[206:209], v197 offset:55296
	ds_read_b128 v[210:213], v197 offset:56320
	s_waitcnt vmcnt(8)
	s_waitcnt lgkmcnt(0)
	s_barrier
	v_mfma_f32_16x16x32_bf16 v[56:59], v[128:131], v[176:179], v[56:59]
	v_mfma_f32_16x16x32_bf16 v[60:63], v[136:139], v[176:179], v[60:63]
	v_mfma_f32_16x16x32_bf16 v[40:43], v[128:131], v[184:187], v[40:43]
	v_mfma_f32_16x16x32_bf16 v[44:47], v[136:139], v[184:187], v[44:47]
	v_mfma_f32_16x16x32_bf16 v[24:27], v[128:131], v[198:201], v[24:27]
	v_mfma_f32_16x16x32_bf16 v[28:31], v[136:139], v[198:201], v[28:31]
	v_mfma_f32_16x16x32_bf16 v[8:11], v[128:131], v[206:209], v[8:11]
	v_mfma_f32_16x16x32_bf16 v[12:15], v[136:139], v[206:209], v[12:15]
	v_mfma_f32_16x16x32_bf16 v[56:59], v[132:135], v[180:183], v[56:59]
	v_mfma_f32_16x16x32_bf16 v[60:63], v[140:143], v[180:183], v[60:63]
	v_mfma_f32_16x16x32_bf16 v[40:43], v[132:135], v[188:191], v[40:43]
	v_mfma_f32_16x16x32_bf16 v[44:47], v[140:143], v[188:191], v[44:47]
	v_mfma_f32_16x16x32_bf16 v[24:27], v[132:135], v[202:205], v[24:27]
	v_mfma_f32_16x16x32_bf16 v[28:31], v[140:143], v[202:205], v[28:31]
	v_mfma_f32_16x16x32_bf16 v[8:11], v[132:135], v[210:213], v[8:11]
	v_mfma_f32_16x16x32_bf16 v[12:15], v[140:143], v[210:213], v[12:15]
	v_mfma_f32_16x16x32_bf16 v[48:51], v[144:147], v[176:179], v[48:51]
	v_mfma_f32_16x16x32_bf16 v[52:55], v[152:155], v[176:179], v[52:55]
	v_mfma_f32_16x16x32_bf16 v[32:35], v[144:147], v[184:187], v[32:35]
	v_mfma_f32_16x16x32_bf16 v[36:39], v[152:155], v[184:187], v[36:39]
	v_mfma_f32_16x16x32_bf16 v[16:19], v[144:147], v[198:201], v[16:19]
	v_mfma_f32_16x16x32_bf16 v[20:23], v[152:155], v[198:201], v[20:23]
	v_mfma_f32_16x16x32_bf16 v[4:7], v[144:147], v[206:209], v[4:7]
	v_mfma_f32_16x16x32_bf16 v[0:3], v[152:155], v[206:209], v[0:3]
	v_mfma_f32_16x16x32_bf16 v[48:51], v[148:151], v[180:183], v[48:51]
	v_mfma_f32_16x16x32_bf16 v[52:55], v[156:159], v[180:183], v[52:55]
	v_mfma_f32_16x16x32_bf16 v[32:35], v[148:151], v[188:191], v[32:35]
	v_mfma_f32_16x16x32_bf16 v[36:39], v[156:159], v[188:191], v[36:39]
	v_mfma_f32_16x16x32_bf16 v[16:19], v[148:151], v[202:205], v[16:19]
	v_mfma_f32_16x16x32_bf16 v[20:23], v[156:159], v[202:205], v[20:23]
	v_mfma_f32_16x16x32_bf16 v[4:7], v[148:151], v[210:213], v[4:7]
	v_mfma_f32_16x16x32_bf16 v[0:3], v[156:159], v[210:213], v[0:3]
	s_barrier
	s_add_i32 s50, s50, 2
	s_add_u32 s48, s48, 0x100
	s_addc_u32 s49, s49, 0
	s_mov_b64 s[20:21], s[2:3]
	v_readlane_b32 s98, v248, 0
	s_nop 3
	s_cmp_ge_u32 s98, 0x100
	s_cbranch_scc1 .Lgprio_skip_5
	s_setprio 1
